# mid-M priority toggles (s_setprio 0 / 2 between the two MFMA halves) removed: one uninterrupted 32-MFMA stream per M phase
# speedup vs baseline: 1.0035x; 1.0035x over previous
; #define PG8_STAGE(bufoff, gbase, voff) do { _Pragma("unroll") for (int _i = 0; _i < 2; ++_i) \
;         __builtin_amdgcn_global_load_lds((const unsigned*)((const char*)(gbase) + (voff)[_i]), (LAS unsigned*)(lds + (bufoff) + ldsw + _i * 8192), 16, 0, 0); } while (0)
; #define PG8_LDA(dst, b, h) do { _Pragma("unroll") for (int m = 0; m < 4; ++m) _Pragma("unroll") for (int k = 0; k < 2; ++k) dst[m][k] = *(const LAS bf16x8*)(lds + PG8_SA(b, h) + aoff + m * 2048 + k * 1024); } while (0)
; #define PG8_LDB(dst, b, h) do { _Pragma("unroll") for (int n = 0; n < 2; ++n) _Pragma("unroll") for (int k = 0; k < 2; ++k) dst[n][k] = *(const LAS bf16x8*)(lds + PG8_SB(b, h) + boff + n * 2048 + k * 1024); } while (0)
; #define PG8_MMA(ai, bj, At, Bt) do { __builtin_amdgcn_s_setprio(3); _Pragma("unroll") for (int m = 0; m < 4; ++m) _Pragma("unroll") for (int n = 0; n < 2; ++n) _Pragma("unroll") for (int k = 0; k < 2; ++k) \
;         acc[ai][bj][m][n] = __builtin_amdgcn_mfma_f32_16x16x32_bf16(Bt[n][k], At[m][k], acc[ai][bj][m][n], 0, 0, 0); __builtin_amdgcn_s_setprio(0); } while (0)
; #define PG8_WAIT_V(n) asm volatile("s_waitcnt vmcnt(" #n ")" ::: "memory")
; #define PG8_WAIT_L(n) asm volatile("s_waitcnt lgkmcnt(" #n ")" ::: "memory")
; #define PG8_BAR __builtin_amdgcn_s_barrier()
; #define PG8_SCHED __builtin_amdgcn_sched_barrier(0)
; template <class Epi, class Sched, bool ALIGN_EPI = false, bool SP2 = false>
; __device__ __forceinline__ void gemm_phase(LAS unsigned char* lds, const Gemm g, const Sched& S, const Epi& E) {
;     ...
;             PG8_LDB(B0, 0, 0); PG8_LDB(B1, 0, 1); PG8_SCHED; PG8_LDA(At, 0, 0); PG8_STAGE(PG8_SA(1, 1), a1 + hsA, voffA);
;             PG8_WAIT_V(8); PG8_WAIT_L(0); PG8_BAR; PG8_MMA(0, 0, At, B0); PG8_MMA(0, 1, At, B1); PG8_BAR; PG8_SCHED;
;             PG8_LDA(At, 0, 1); PG8_STAGE(PG8_SB(0, 0), b2, voffB); PG8_STAGE(PG8_SB(0, 1), b2 + hsB, voffB); PG8_STAGE(PG8_SA(0, 0), a2, voffA);
;             PG8_WAIT_V(8); PG8_WAIT_L(0); PG8_BAR; PG8_MMA(1, 0, At, B0); PG8_MMA(1, 1, At, B1); PG8_BAR; PG8_SCHED;
.LBB0_64:
	ds_read_b128 v[128:131], v158
	ds_read_b128 v[150:153], v251
	ds_read_b128 v[166:169], v158 offset:2048
	ds_read_b128 v[170:173], v251 offset:2048
	ds_read_b128 v[174:177], v159
	ds_read_b128 v[178:181], v252
	ds_read_b128 v[182:185], v159 offset:2048
	ds_read_b128 v[186:189], v252 offset:2048
	s_add_u32 s6, s4, 0xffefc080
	s_addc_u32 s7, s5, -1
	s_cmp_eq_u32 s91, 60
	s_cselect_b32 s63, s59, s7
	s_cselect_b32 s62, s58, s6
	s_cselect_b32 s7, s61, s90
	s_cselect_b32 s6, s60, s89
	s_sub_u32 s100, s4, 0x104000
	s_subb_u32 s101, s5, 0
	s_mov_b32 m0, s76
	ds_read_b128 v[214:217], v250 offset:4096
	global_load_lds_dwordx4 v132, s[100:101]
	s_mov_b32 m0, s77
	ds_read_b128 v[218:221], v160 offset:6144
	global_load_lds_dwordx4 v136, s[100:101]
	s_add_i32 m0, s68, 0xc000
	ds_read_b128 v[190:193], v160
	ds_read_b128 v[194:197], v250
	ds_read_b128 v[198:201], v160 offset:2048
	ds_read_b128 v[206:209], v250 offset:2048
	ds_read_b128 v[210:213], v160 offset:4096
	global_load_lds_dwordx4 v142, s[4:5]
	s_add_i32 m0, s68, 0xe000
	ds_read_b128 v[222:225], v250 offset:6144
	global_load_lds_dwordx4 v144, s[4:5]
	s_waitcnt vmcnt(8)
	s_waitcnt lgkmcnt(0)
	s_setprio 2
	s_barrier
	v_mfma_f32_16x16x32_bf16 v[124:127], v[128:131], v[190:193], v[124:127]
	v_mfma_f32_16x16x32_bf16 v[124:127], v[150:153], v[194:197], v[124:127]
	v_mfma_f32_16x16x32_bf16 v[120:123], v[166:169], v[190:193], v[120:123]
	v_mfma_f32_16x16x32_bf16 v[120:123], v[170:173], v[194:197], v[120:123]
	v_mfma_f32_16x16x32_bf16 v[108:111], v[128:131], v[198:201], v[108:111]
	v_mfma_f32_16x16x32_bf16 v[108:111], v[150:153], v[206:209], v[108:111]
	v_mfma_f32_16x16x32_bf16 v[104:107], v[166:169], v[198:201], v[104:107]
	v_mfma_f32_16x16x32_bf16 v[104:107], v[170:173], v[206:209], v[104:107]
	v_mfma_f32_16x16x32_bf16 v[92:95], v[128:131], v[210:213], v[92:95]
	v_mfma_f32_16x16x32_bf16 v[92:95], v[150:153], v[214:217], v[92:95]
	v_mfma_f32_16x16x32_bf16 v[88:91], v[166:169], v[210:213], v[88:91]
	v_mfma_f32_16x16x32_bf16 v[88:91], v[170:173], v[214:217], v[88:91]
	v_mfma_f32_16x16x32_bf16 v[76:79], v[128:131], v[218:221], v[76:79]
	v_mfma_f32_16x16x32_bf16 v[76:79], v[150:153], v[222:225], v[76:79]
	v_mfma_f32_16x16x32_bf16 v[72:75], v[166:169], v[218:221], v[72:75]
	v_mfma_f32_16x16x32_bf16 v[72:75], v[170:173], v[222:225], v[72:75]
	v_mfma_f32_16x16x32_bf16 v[116:119], v[174:177], v[190:193], v[116:119]
	v_mfma_f32_16x16x32_bf16 v[116:119], v[178:181], v[194:197], v[116:119]
	v_mfma_f32_16x16x32_bf16 v[112:115], v[182:185], v[190:193], v[112:115]
	v_mfma_f32_16x16x32_bf16 v[112:115], v[186:189], v[194:197], v[112:115]
	v_mfma_f32_16x16x32_bf16 v[100:103], v[174:177], v[198:201], v[100:103]
	v_mfma_f32_16x16x32_bf16 v[100:103], v[178:181], v[206:209], v[100:103]
	v_mfma_f32_16x16x32_bf16 v[96:99], v[182:185], v[198:201], v[96:99]
	v_mfma_f32_16x16x32_bf16 v[96:99], v[186:189], v[206:209], v[96:99]
	v_mfma_f32_16x16x32_bf16 v[84:87], v[174:177], v[210:213], v[84:87]
	v_mfma_f32_16x16x32_bf16 v[84:87], v[178:181], v[214:217], v[84:87]
	v_mfma_f32_16x16x32_bf16 v[80:83], v[182:185], v[210:213], v[80:83]
	v_mfma_f32_16x16x32_bf16 v[80:83], v[186:189], v[214:217], v[80:83]
	v_mfma_f32_16x16x32_bf16 v[68:71], v[174:177], v[218:221], v[68:71]
	v_mfma_f32_16x16x32_bf16 v[68:71], v[178:181], v[222:225], v[68:71]
	v_mfma_f32_16x16x32_bf16 v[64:67], v[182:185], v[218:221], v[64:67]
	s_setprio 3
	s_barrier
	v_mfma_f32_16x16x32_bf16 v[64:67], v[186:189], v[222:225], v[64:67]
	s_setprio 0
	s_add_i32 s92, s82, s67
	s_mov_b32 m0, s92
	ds_read_b128 v[190:193], v160 offset:16384
	ds_read_b128 v[194:197], v250 offset:16384
	ds_read_b128 v[198:201], v160 offset:18432
	ds_read_b128 v[206:209], v250 offset:18432
	ds_read_b128 v[210:213], v160 offset:20480
	ds_read_b128 v[214:217], v250 offset:20480
	global_load_lds_dwordx4 v134, s[6:7]
	s_add_i32 m0, s92, 0x2000
	s_add_u32 s92, s6, 0x41000
	s_addc_u32 s93, s7, 0
	s_add_i32 s94, s83, s67
	global_load_lds_dwordx4 v138, s[6:7]
	s_mov_b32 m0, s94
	ds_read_b128 v[218:221], v160 offset:22528
	global_load_lds_dwordx4 v134, s[92:93]
	s_add_i32 m0, s94, 0x2000
	ds_read_b128 v[222:225], v250 offset:22528
	global_load_lds_dwordx4 v138, s[92:93]
	s_waitcnt vmcnt(6)
	s_waitcnt lgkmcnt(0)
	s_setprio 2
	s_barrier
	v_mfma_f32_16x16x32_bf16 v[60:63], v[128:131], v[190:193], v[60:63]
	v_mfma_f32_16x16x32_bf16 v[60:63], v[150:153], v[194:197], v[60:63]
	v_mfma_f32_16x16x32_bf16 v[56:59], v[166:169], v[190:193], v[56:59]
	v_mfma_f32_16x16x32_bf16 v[56:59], v[170:173], v[194:197], v[56:59]
	v_mfma_f32_16x16x32_bf16 v[44:47], v[128:131], v[198:201], v[44:47]
	v_mfma_f32_16x16x32_bf16 v[44:47], v[150:153], v[206:209], v[44:47]
	v_mfma_f32_16x16x32_bf16 v[40:43], v[166:169], v[198:201], v[40:43]
	v_mfma_f32_16x16x32_bf16 v[40:43], v[170:173], v[206:209], v[40:43]
	v_mfma_f32_16x16x32_bf16 v[28:31], v[128:131], v[210:213], v[28:31]
	v_mfma_f32_16x16x32_bf16 v[28:31], v[150:153], v[214:217], v[28:31]
	v_mfma_f32_16x16x32_bf16 v[24:27], v[166:169], v[210:213], v[24:27]
	v_mfma_f32_16x16x32_bf16 v[24:27], v[170:173], v[214:217], v[24:27]
	v_mfma_f32_16x16x32_bf16 v[12:15], v[128:131], v[218:221], v[12:15]
	v_mfma_f32_16x16x32_bf16 v[12:15], v[150:153], v[222:225], v[12:15]
	v_mfma_f32_16x16x32_bf16 v[8:11], v[166:169], v[218:221], v[8:11]
	v_mfma_f32_16x16x32_bf16 v[8:11], v[170:173], v[222:225], v[8:11]
	v_mfma_f32_16x16x32_bf16 v[52:55], v[174:177], v[190:193], v[52:55]
	v_mfma_f32_16x16x32_bf16 v[52:55], v[178:181], v[194:197], v[52:55]
	v_mfma_f32_16x16x32_bf16 v[48:51], v[182:185], v[190:193], v[48:51]
	v_mfma_f32_16x16x32_bf16 v[48:51], v[186:189], v[194:197], v[48:51]
	v_mfma_f32_16x16x32_bf16 v[36:39], v[174:177], v[198:201], v[36:39]
	v_mfma_f32_16x16x32_bf16 v[36:39], v[178:181], v[206:209], v[36:39]
	v_mfma_f32_16x16x32_bf16 v[32:35], v[182:185], v[198:201], v[32:35]
	v_mfma_f32_16x16x32_bf16 v[32:35], v[186:189], v[206:209], v[32:35]
	v_mfma_f32_16x16x32_bf16 v[20:23], v[174:177], v[210:213], v[20:23]
	v_mfma_f32_16x16x32_bf16 v[20:23], v[178:181], v[214:217], v[20:23]
	v_mfma_f32_16x16x32_bf16 v[16:19], v[182:185], v[210:213], v[16:19]
	v_mfma_f32_16x16x32_bf16 v[16:19], v[186:189], v[214:217], v[16:19]
	v_mfma_f32_16x16x32_bf16 v[4:7], v[174:177], v[218:221], v[4:7]
	v_mfma_f32_16x16x32_bf16 v[4:7], v[178:181], v[222:225], v[4:7]
	v_mfma_f32_16x16x32_bf16 v[0:3], v[182:185], v[218:221], v[0:3]
	s_setprio 3
	s_barrier
; #define PG8_STAGE(bufoff, gbase, voff) do { _Pragma("unroll") for (int _i = 0; _i < 2; ++_i) \
;         __builtin_amdgcn_global_load_lds((const unsigned*)((const char*)(gbase) + (voff)[_i]), (LAS unsigned*)(lds + (bufoff) + ldsw + _i * 8192), 16, 0, 0); } while (0)
; #define PG8_LDA(dst, b, h) do { _Pragma("unroll") for (int m = 0; m < 4; ++m) _Pragma("unroll") for (int k = 0; k < 2; ++k) dst[m][k] = *(const LAS bf16x8*)(lds + PG8_SA(b, h) + aoff + m * 2048 + k * 1024); } while (0)
; #define PG8_LDB(dst, b, h) do { _Pragma("unroll") for (int n = 0; n < 2; ++n) _Pragma("unroll") for (int k = 0; k < 2; ++k) dst[n][k] = *(const LAS bf16x8*)(lds + PG8_SB(b, h) + boff + n * 2048 + k * 1024); } while (0)
; #define PG8_MMA(ai, bj, At, Bt) do { __builtin_amdgcn_s_setprio(3); _Pragma("unroll") for (int m = 0; m < 4; ++m) _Pragma("unroll") for (int n = 0; n < 2; ++n) _Pragma("unroll") for (int k = 0; k < 2; ++k) \
;         acc[ai][bj][m][n] = __builtin_amdgcn_mfma_f32_16x16x32_bf16(Bt[n][k], At[m][k], acc[ai][bj][m][n], 0, 0, 0); __builtin_amdgcn_s_setprio(0); } while (0)
; #define PG8_WAIT_V(n) asm volatile("s_waitcnt vmcnt(" #n ")" ::: "memory")
; #define PG8_WAIT_L(n) asm volatile("s_waitcnt lgkmcnt(" #n ")" ::: "memory")
; #define PG8_BAR __builtin_amdgcn_s_barrier()
; #define PG8_SCHED __builtin_amdgcn_sched_barrier(0)
; template <class Epi, class Sched, bool ALIGN_EPI = false, bool SP2 = false>
; __device__ __forceinline__ void gemm_phase(LAS unsigned char* lds, const Gemm g, const Sched& S, const Epi& E) {
;     ...
;             PG8_LDB(B0, 1, 0); PG8_LDB(B1, 1, 1); PG8_SCHED; PG8_LDA(At, 1, 0); PG8_STAGE(PG8_SA(0, 1), a2 + hsA, voffA);
;             PG8_WAIT_V(8); PG8_WAIT_L(0); PG8_BAR; PG8_MMA(0, 0, At, B0); PG8_MMA(0, 1, At, B1); PG8_BAR; PG8_SCHED;
;             PG8_LDA(At, 1, 1); PG8_STAGE(PG8_SB(1, 0), b3, voffB); PG8_STAGE(PG8_SB(1, 1), b3 + hsB, voffB); PG8_STAGE(PG8_SA(1, 0), a3, voffA);
;             PG8_WAIT_V(8); PG8_WAIT_L(0); PG8_BAR; PG8_MMA(1, 0, At, B0); PG8_MMA(1, 1, At, B1); PG8_BAR; PG8_SCHED;
	v_mfma_f32_16x16x32_bf16 v[0:3], v[186:189], v[222:225], v[0:3]
	s_setprio 0
	s_add_i32 s92, 0, 0x18000
	s_add_i32 s93, 0, 0x1c000
	ds_read_b128 v[128:131], v246
	ds_read_b128 v[150:153], v247
	ds_read_b128 v[166:169], v246 offset:2048
	ds_read_b128 v[170:173], v247 offset:2048
	ds_read_b128 v[174:177], v248
	ds_read_b128 v[178:181], v249
	ds_read_b128 v[182:185], v248 offset:2048
	ds_read_b128 v[186:189], v249 offset:2048
	s_mov_b32 m0, s68
	ds_read_b128 v[214:217], v250 offset:36864
	global_load_lds_dwordx4 v132, s[62:63]
	s_mov_b32 m0, s69
	ds_read_b128 v[218:221], v160 offset:38912
	global_load_lds_dwordx4 v136, s[62:63]
	s_add_u32 s62, s62, 0x104000
	s_addc_u32 s63, s63, 0
	s_mov_b32 m0, s70
	ds_read_b128 v[190:193], v160 offset:32768
	ds_read_b128 v[194:197], v250 offset:32768
	ds_read_b128 v[198:201], v160 offset:34816
	ds_read_b128 v[206:209], v250 offset:34816
	ds_read_b128 v[210:213], v160 offset:36864
	global_load_lds_dwordx4 v132, s[62:63]
	s_mov_b32 m0, s71
	ds_read_b128 v[222:225], v250 offset:38912
	global_load_lds_dwordx4 v136, s[62:63]
	s_waitcnt vmcnt(8)
	s_waitcnt lgkmcnt(0)
	s_setprio 2
	s_barrier
	v_mfma_f32_16x16x32_bf16 v[124:127], v[128:131], v[190:193], v[124:127]
	v_mfma_f32_16x16x32_bf16 v[124:127], v[150:153], v[194:197], v[124:127]
	v_mfma_f32_16x16x32_bf16 v[120:123], v[166:169], v[190:193], v[120:123]
	v_mfma_f32_16x16x32_bf16 v[120:123], v[170:173], v[194:197], v[120:123]
	v_mfma_f32_16x16x32_bf16 v[108:111], v[128:131], v[198:201], v[108:111]
	v_mfma_f32_16x16x32_bf16 v[108:111], v[150:153], v[206:209], v[108:111]
	v_mfma_f32_16x16x32_bf16 v[104:107], v[166:169], v[198:201], v[104:107]
	v_mfma_f32_16x16x32_bf16 v[104:107], v[170:173], v[206:209], v[104:107]
	v_mfma_f32_16x16x32_bf16 v[92:95], v[128:131], v[210:213], v[92:95]
	v_mfma_f32_16x16x32_bf16 v[92:95], v[150:153], v[214:217], v[92:95]
	v_mfma_f32_16x16x32_bf16 v[88:91], v[166:169], v[210:213], v[88:91]
	v_mfma_f32_16x16x32_bf16 v[88:91], v[170:173], v[214:217], v[88:91]
	v_mfma_f32_16x16x32_bf16 v[76:79], v[128:131], v[218:221], v[76:79]
	v_mfma_f32_16x16x32_bf16 v[76:79], v[150:153], v[222:225], v[76:79]
	v_mfma_f32_16x16x32_bf16 v[72:75], v[166:169], v[218:221], v[72:75]
	v_mfma_f32_16x16x32_bf16 v[72:75], v[170:173], v[222:225], v[72:75]
	v_mfma_f32_16x16x32_bf16 v[116:119], v[174:177], v[190:193], v[116:119]
	v_mfma_f32_16x16x32_bf16 v[116:119], v[178:181], v[194:197], v[116:119]
	v_mfma_f32_16x16x32_bf16 v[112:115], v[182:185], v[190:193], v[112:115]
	v_mfma_f32_16x16x32_bf16 v[112:115], v[186:189], v[194:197], v[112:115]
	v_mfma_f32_16x16x32_bf16 v[100:103], v[174:177], v[198:201], v[100:103]
	v_mfma_f32_16x16x32_bf16 v[100:103], v[178:181], v[206:209], v[100:103]
	v_mfma_f32_16x16x32_bf16 v[96:99], v[182:185], v[198:201], v[96:99]
	v_mfma_f32_16x16x32_bf16 v[96:99], v[186:189], v[206:209], v[96:99]
	v_mfma_f32_16x16x32_bf16 v[84:87], v[174:177], v[210:213], v[84:87]
	v_mfma_f32_16x16x32_bf16 v[84:87], v[178:181], v[214:217], v[84:87]
	v_mfma_f32_16x16x32_bf16 v[80:83], v[182:185], v[210:213], v[80:83]
	v_mfma_f32_16x16x32_bf16 v[80:83], v[186:189], v[214:217], v[80:83]
	v_mfma_f32_16x16x32_bf16 v[68:71], v[174:177], v[218:221], v[68:71]
	v_mfma_f32_16x16x32_bf16 v[68:71], v[178:181], v[222:225], v[68:71]
	v_mfma_f32_16x16x32_bf16 v[64:67], v[182:185], v[218:221], v[64:67]
	s_setprio 3
	s_barrier
	v_mfma_f32_16x16x32_bf16 v[64:67], v[186:189], v[222:225], v[64:67]
	s_setprio 0
	s_add_i32 s62, s92, s67
	s_add_u32 s100, s6, s46
	s_addc_u32 s101, s7, s47
	s_mov_b32 m0, s62
	ds_read_b128 v[190:193], v160 offset:49152
	ds_read_b128 v[194:197], v250 offset:49152
	ds_read_b128 v[198:201], v160 offset:51200
	ds_read_b128 v[206:209], v250 offset:51200
	ds_read_b128 v[210:213], v160 offset:53248
	ds_read_b128 v[214:217], v250 offset:53248
	global_load_lds_dwordx4 v134, s[100:101]
	s_add_i32 m0, s62, 0x2000
	s_add_u32 s6, s6, 0x41080
	s_addc_u32 s7, s7, 0
	s_add_i32 s62, s93, s67
	global_load_lds_dwordx4 v138, s[100:101]
	s_mov_b32 m0, s62
	ds_read_b128 v[218:221], v160 offset:55296
	global_load_lds_dwordx4 v134, s[6:7]
	s_add_i32 m0, s62, 0x2000
	ds_read_b128 v[222:225], v250 offset:55296
	global_load_lds_dwordx4 v138, s[6:7]
	s_waitcnt vmcnt(6)
	s_waitcnt lgkmcnt(0)
	s_setprio 2
	s_barrier
	v_mfma_f32_16x16x32_bf16 v[60:63], v[128:131], v[190:193], v[60:63]
	v_mfma_f32_16x16x32_bf16 v[60:63], v[150:153], v[194:197], v[60:63]
	v_mfma_f32_16x16x32_bf16 v[56:59], v[166:169], v[190:193], v[56:59]
	v_mfma_f32_16x16x32_bf16 v[56:59], v[170:173], v[194:197], v[56:59]
	v_mfma_f32_16x16x32_bf16 v[44:47], v[128:131], v[198:201], v[44:47]
	v_mfma_f32_16x16x32_bf16 v[44:47], v[150:153], v[206:209], v[44:47]
	v_mfma_f32_16x16x32_bf16 v[40:43], v[166:169], v[198:201], v[40:43]
	v_mfma_f32_16x16x32_bf16 v[40:43], v[170:173], v[206:209], v[40:43]
	v_mfma_f32_16x16x32_bf16 v[28:31], v[128:131], v[210:213], v[28:31]
	v_mfma_f32_16x16x32_bf16 v[28:31], v[150:153], v[214:217], v[28:31]
	v_mfma_f32_16x16x32_bf16 v[24:27], v[166:169], v[210:213], v[24:27]
	v_mfma_f32_16x16x32_bf16 v[24:27], v[170:173], v[214:217], v[24:27]
	v_mfma_f32_16x16x32_bf16 v[12:15], v[128:131], v[218:221], v[12:15]
	v_mfma_f32_16x16x32_bf16 v[12:15], v[150:153], v[222:225], v[12:15]
	v_mfma_f32_16x16x32_bf16 v[8:11], v[166:169], v[218:221], v[8:11]
	v_mfma_f32_16x16x32_bf16 v[8:11], v[170:173], v[222:225], v[8:11]
	v_mfma_f32_16x16x32_bf16 v[52:55], v[174:177], v[190:193], v[52:55]
	v_mfma_f32_16x16x32_bf16 v[52:55], v[178:181], v[194:197], v[52:55]
	v_mfma_f32_16x16x32_bf16 v[48:51], v[182:185], v[190:193], v[48:51]
	v_mfma_f32_16x16x32_bf16 v[48:51], v[186:189], v[194:197], v[48:51]
	v_mfma_f32_16x16x32_bf16 v[36:39], v[174:177], v[198:201], v[36:39]
	v_mfma_f32_16x16x32_bf16 v[36:39], v[178:181], v[206:209], v[36:39]
	v_mfma_f32_16x16x32_bf16 v[32:35], v[182:185], v[198:201], v[32:35]
	v_mfma_f32_16x16x32_bf16 v[32:35], v[186:189], v[206:209], v[32:35]
	v_mfma_f32_16x16x32_bf16 v[20:23], v[174:177], v[210:213], v[20:23]
	v_mfma_f32_16x16x32_bf16 v[20:23], v[178:181], v[214:217], v[20:23]
	v_mfma_f32_16x16x32_bf16 v[16:19], v[182:185], v[210:213], v[16:19]
	v_mfma_f32_16x16x32_bf16 v[16:19], v[186:189], v[214:217], v[16:19]
	v_mfma_f32_16x16x32_bf16 v[4:7], v[174:177], v[218:221], v[4:7]
	v_mfma_f32_16x16x32_bf16 v[4:7], v[178:181], v[222:225], v[4:7]
	v_mfma_f32_16x16x32_bf16 v[0:3], v[182:185], v[218:221], v[0:3]
	s_setprio 3
	s_barrier
	v_mfma_f32_16x16x32_bf16 v[0:3], v[186:189], v[222:225], v[0:3]
	s_setprio 0
	s_add_i32 s91, s91, 2
	s_add_u32 s4, s4, 0x100
	s_addc_u32 s5, s5, 0
	s_add_u32 s89, s89, 0x100
	s_addc_u32 s90, s90, 0
	s_cmp_gt_u32 s91, 61
	s_cbranch_scc0 .LBB0_64
	s_and_b64 vcc, exec, s[50:51]
	s_cbranch_vccz .LBB0_67
	s_barrier

; #define PG8_STAGE(bufoff, gbase, voff) do { _Pragma("unroll") for (int _i = 0; _i < 2; ++_i) \
;         __builtin_amdgcn_global_load_lds((const unsigned*)((const char*)(gbase) + (voff)[_i]), (LAS unsigned*)(lds + (bufoff) + ldsw + _i * 8192), 16, 0, 0); } while (0)
; #define PG8_LDA(dst, b, h) do { _Pragma("unroll") for (int m = 0; m < 4; ++m) _Pragma("unroll") for (int k = 0; k < 2; ++k) dst[m][k] = *(const LAS bf16x8*)(lds + PG8_SA(b, h) + aoff + m * 2048 + k * 1024); } while (0)
; #define PG8_LDB(dst, b, h) do { _Pragma("unroll") for (int n = 0; n < 2; ++n) _Pragma("unroll") for (int k = 0; k < 2; ++k) dst[n][k] = *(const LAS bf16x8*)(lds + PG8_SB(b, h) + boff + n * 2048 + k * 1024); } while (0)
; #define PG8_MMA(ai, bj, At, Bt) do { __builtin_amdgcn_s_setprio(3); _Pragma("unroll") for (int m = 0; m < 4; ++m) _Pragma("unroll") for (int n = 0; n < 2; ++n) _Pragma("unroll") for (int k = 0; k < 2; ++k) \
;         acc[ai][bj][m][n] = __builtin_amdgcn_mfma_f32_16x16x32_bf16(Bt[n][k], At[m][k], acc[ai][bj][m][n], 0, 0, 0); __builtin_amdgcn_s_setprio(0); } while (0)
; #define PG8_WAIT_V(n) asm volatile("s_waitcnt vmcnt(" #n ")" ::: "memory")
; #define PG8_WAIT_L(n) asm volatile("s_waitcnt lgkmcnt(" #n ")" ::: "memory")
; #define PG8_BAR __builtin_amdgcn_s_barrier()
; #define PG8_SCHED __builtin_amdgcn_sched_barrier(0)
; template <class Epi, class Sched, bool ALIGN_EPI = false, bool SP2 = false>
; __device__ __forceinline__ void gemm_phase(LAS unsigned char* lds, const Gemm g, const Sched& S, const Epi& E) {
;     ...
;             PG8_LDB(B0, 0, 0); PG8_LDB(B1, 0, 1); PG8_SCHED; PG8_LDA(At, 0, 0); PG8_STAGE(PG8_SA(1, 1), a1 + hsA, voffA);
;             PG8_WAIT_V(8); PG8_WAIT_L(0); PG8_BAR; PG8_MMA(0, 0, At, B0); PG8_MMA(0, 1, At, B1); PG8_BAR; PG8_SCHED;
;             PG8_LDA(At, 0, 1); PG8_STAGE(PG8_SB(0, 0), b2, voffB); PG8_STAGE(PG8_SB(0, 1), b2 + hsB, voffB); PG8_STAGE(PG8_SA(0, 0), a2, voffA);
;             PG8_WAIT_V(8); PG8_WAIT_L(0); PG8_BAR; PG8_MMA(1, 0, At, B0); PG8_MMA(1, 1, At, B1); PG8_BAR; PG8_SCHED;
.LBB0_234:
	v_add_u32_e32 v1, s88, v194
	v_xor_b32_e32 v253, 64, v1
	ds_read_b128 v[84:87], v1
	ds_read_b128 v[96:99], v253
	ds_read_b128 v[140:143], v1 offset:2048
	ds_read_b128 v[144:147], v253 offset:2048
	v_add_u32_e32 v1, s89, v194
	v_xor_b32_e32 v253, 64, v1
	s_add_u32 s4, s64, s66
	ds_read_b128 v[152:155], v1
	ds_read_b128 v[156:159], v253
	ds_read_b128 v[160:163], v1 offset:2048
	ds_read_b128 v[182:185], v253 offset:2048
	s_addc_u32 s5, s65, s67
	s_add_u32 s4, s4, 0x100
	s_addc_u32 s5, s5, 0
	s_add_u32 s96, s93, s66
	s_addc_u32 s97, s94, s67
	s_cmpk_eq_i32 s66, 0x1f00
	s_cselect_b32 s9, s59, s5
	s_cselect_b32 s8, s91, s4
	s_cselect_b32 s5, s61, s97
	s_cselect_b32 s4, s60, s96
	s_sub_u32 s100, s66, 0x100000
	s_subb_u32 s101, s67, 0
	v_lshl_add_u64 v[242:243], v[148:149], 0, s[100:101]
	s_mov_b32 m0, s81
	v_lshl_add_u64 v[244:245], v[150:151], 0, s[100:101]
	global_load_lds_dwordx4 v[242:243], off
	s_mov_b32 m0, s82
	ds_read_b128 v[228:231], v198 offset:6144
	global_load_lds_dwordx4 v[244:245], off
	v_lshl_add_u64 v[2:3], v[148:149], 0, s[66:67]
	s_add_i32 m0, s41, 0xc000
	ds_read_b128 v[186:189], v198
	ds_read_b128 v[208:211], v250
	ds_read_b128 v[212:215], v198 offset:2048
	ds_read_b128 v[216:219], v250 offset:2048
	ds_read_b128 v[220:223], v198 offset:4096
	ds_read_b128 v[224:227], v250 offset:4096
	global_load_lds_dwordx4 v[2:3], off
	v_lshl_add_u64 v[2:3], v[150:151], 0, s[66:67]
	s_add_i32 m0, s41, 0xe000
	ds_read_b128 v[232:235], v250 offset:6144
	global_load_lds_dwordx4 v[2:3], off
	s_waitcnt vmcnt(8)
	s_waitcnt lgkmcnt(0)
	s_setprio 2
	s_barrier
	v_mfma_f32_16x16x32_bf16 v[136:139], v[84:87], v[186:189], v[136:139]
	v_mfma_f32_16x16x32_bf16 v[136:139], v[96:99], v[208:211], v[136:139]
	v_mfma_f32_16x16x32_bf16 v[132:135], v[140:143], v[186:189], v[132:135]
	v_mfma_f32_16x16x32_bf16 v[132:135], v[144:147], v[208:211], v[132:135]
	v_mfma_f32_16x16x32_bf16 v[120:123], v[84:87], v[212:215], v[120:123]
	v_mfma_f32_16x16x32_bf16 v[120:123], v[96:99], v[216:219], v[120:123]
	v_mfma_f32_16x16x32_bf16 v[116:119], v[140:143], v[212:215], v[116:119]
	v_mfma_f32_16x16x32_bf16 v[116:119], v[144:147], v[216:219], v[116:119]
	v_mfma_f32_16x16x32_bf16 v[104:107], v[84:87], v[220:223], v[104:107]
	v_mfma_f32_16x16x32_bf16 v[104:107], v[96:99], v[224:227], v[104:107]
	v_mfma_f32_16x16x32_bf16 v[100:103], v[140:143], v[220:223], v[100:103]
	v_mfma_f32_16x16x32_bf16 v[100:103], v[144:147], v[224:227], v[100:103]
	v_mfma_f32_16x16x32_bf16 v[80:83], v[84:87], v[228:231], v[80:83]
	v_mfma_f32_16x16x32_bf16 v[80:83], v[96:99], v[232:235], v[80:83]
	v_mfma_f32_16x16x32_bf16 v[76:79], v[140:143], v[228:231], v[76:79]
	v_mfma_f32_16x16x32_bf16 v[76:79], v[144:147], v[232:235], v[76:79]
	v_mfma_f32_16x16x32_bf16 v[128:131], v[152:155], v[186:189], v[128:131]
	v_mfma_f32_16x16x32_bf16 v[128:131], v[156:159], v[208:211], v[128:131]
	v_mfma_f32_16x16x32_bf16 v[124:127], v[160:163], v[186:189], v[124:127]
	v_mfma_f32_16x16x32_bf16 v[124:127], v[182:185], v[208:211], v[124:127]
	v_mfma_f32_16x16x32_bf16 v[112:115], v[152:155], v[212:215], v[112:115]
	v_mfma_f32_16x16x32_bf16 v[112:115], v[156:159], v[216:219], v[112:115]
	v_mfma_f32_16x16x32_bf16 v[108:111], v[160:163], v[212:215], v[108:111]
	v_mfma_f32_16x16x32_bf16 v[108:111], v[182:185], v[216:219], v[108:111]
	v_mfma_f32_16x16x32_bf16 v[92:95], v[152:155], v[220:223], v[92:95]
	v_mfma_f32_16x16x32_bf16 v[92:95], v[156:159], v[224:227], v[92:95]
	v_mfma_f32_16x16x32_bf16 v[88:91], v[160:163], v[220:223], v[88:91]
	v_mfma_f32_16x16x32_bf16 v[88:91], v[182:185], v[224:227], v[88:91]
	v_mfma_f32_16x16x32_bf16 v[72:75], v[152:155], v[228:231], v[72:75]
	v_mfma_f32_16x16x32_bf16 v[72:75], v[156:159], v[232:235], v[72:75]
	v_mfma_f32_16x16x32_bf16 v[68:71], v[160:163], v[228:231], v[68:71]
	s_setprio 3
	s_barrier
	v_mfma_f32_16x16x32_bf16 v[68:71], v[182:185], v[232:235], v[68:71]
	s_setprio 0
	s_add_i32 s96, s88, s31
	s_mov_b32 m0, s96
	ds_read_b128 v[186:189], v198 offset:16384
	ds_read_b128 v[208:211], v250 offset:16384
	ds_read_b128 v[212:215], v198 offset:18432
	ds_read_b128 v[216:219], v250 offset:18432
	ds_read_b128 v[220:223], v198 offset:20480
	ds_read_b128 v[224:227], v250 offset:20480
	global_load_lds_dwordx4 v166, s[4:5]
	s_add_i32 m0, s96, 0x2000
	s_add_u32 s96, s4, 0x104000
	s_addc_u32 s97, s5, 0
	s_add_i32 s98, s89, s31
	global_load_lds_dwordx4 v170, s[4:5]
	s_mov_b32 m0, s98
	ds_read_b128 v[228:231], v198 offset:22528
	global_load_lds_dwordx4 v166, s[96:97]
	s_add_i32 m0, s98, 0x2000
	ds_read_b128 v[232:235], v250 offset:22528
	global_load_lds_dwordx4 v170, s[96:97]
	s_waitcnt vmcnt(6)
	s_waitcnt lgkmcnt(0)
	s_setprio 2
	s_barrier
; #define PG8_STAGE(bufoff, gbase, voff) do { _Pragma("unroll") for (int _i = 0; _i < 2; ++_i) \
;         __builtin_amdgcn_global_load_lds((const unsigned*)((const char*)(gbase) + (voff)[_i]), (LAS unsigned*)(lds + (bufoff) + ldsw + _i * 8192), 16, 0, 0); } while (0)
; #define PG8_LDA(dst, b, h) do { _Pragma("unroll") for (int m = 0; m < 4; ++m) _Pragma("unroll") for (int k = 0; k < 2; ++k) dst[m][k] = *(const LAS bf16x8*)(lds + PG8_SA(b, h) + aoff + m * 2048 + k * 1024); } while (0)
; #define PG8_LDB(dst, b, h) do { _Pragma("unroll") for (int n = 0; n < 2; ++n) _Pragma("unroll") for (int k = 0; k < 2; ++k) dst[n][k] = *(const LAS bf16x8*)(lds + PG8_SB(b, h) + boff + n * 2048 + k * 1024); } while (0)
; #define PG8_MMA(ai, bj, At, Bt) do { __builtin_amdgcn_s_setprio(3); _Pragma("unroll") for (int m = 0; m < 4; ++m) _Pragma("unroll") for (int n = 0; n < 2; ++n) _Pragma("unroll") for (int k = 0; k < 2; ++k) \
;         acc[ai][bj][m][n] = __builtin_amdgcn_mfma_f32_16x16x32_bf16(Bt[n][k], At[m][k], acc[ai][bj][m][n], 0, 0, 0); __builtin_amdgcn_s_setprio(0); } while (0)
; #define PG8_WAIT_V(n) asm volatile("s_waitcnt vmcnt(" #n ")" ::: "memory")
; #define PG8_WAIT_L(n) asm volatile("s_waitcnt lgkmcnt(" #n ")" ::: "memory")
; #define PG8_BAR __builtin_amdgcn_s_barrier()
; #define PG8_SCHED __builtin_amdgcn_sched_barrier(0)
; template <class Epi, class Sched, bool ALIGN_EPI = false, bool SP2 = false>
; __device__ __forceinline__ void gemm_phase(LAS unsigned char* lds, const Gemm g, const Sched& S, const Epi& E) {
;     ...
;             PG8_WAIT_V(8); PG8_WAIT_L(0); PG8_BAR; PG8_MMA(1, 0, At, B0); PG8_MMA(1, 1, At, B1); PG8_BAR; PG8_SCHED;
;             PG8_LDB(B0, 1, 0); PG8_LDB(B1, 1, 1); PG8_SCHED; PG8_LDA(At, 1, 0); PG8_STAGE(PG8_SA(0, 1), a2 + hsA, voffA);
;             PG8_WAIT_V(8); PG8_WAIT_L(0); PG8_BAR; PG8_MMA(0, 0, At, B0); PG8_MMA(0, 1, At, B1); PG8_BAR; PG8_SCHED;
	v_mfma_f32_16x16x32_bf16 v[64:67], v[84:87], v[186:189], v[64:67]
	v_mfma_f32_16x16x32_bf16 v[64:67], v[96:99], v[208:211], v[64:67]
	v_mfma_f32_16x16x32_bf16 v[60:63], v[140:143], v[186:189], v[60:63]
	v_mfma_f32_16x16x32_bf16 v[60:63], v[144:147], v[208:211], v[60:63]
	v_mfma_f32_16x16x32_bf16 v[48:51], v[84:87], v[212:215], v[48:51]
	v_mfma_f32_16x16x32_bf16 v[48:51], v[96:99], v[216:219], v[48:51]
	v_mfma_f32_16x16x32_bf16 v[44:47], v[140:143], v[212:215], v[44:47]
	v_mfma_f32_16x16x32_bf16 v[44:47], v[144:147], v[216:219], v[44:47]
	v_mfma_f32_16x16x32_bf16 v[32:35], v[84:87], v[220:223], v[32:35]
	v_mfma_f32_16x16x32_bf16 v[32:35], v[96:99], v[224:227], v[32:35]
	v_mfma_f32_16x16x32_bf16 v[28:31], v[140:143], v[220:223], v[28:31]
	v_mfma_f32_16x16x32_bf16 v[28:31], v[144:147], v[224:227], v[28:31]
	v_mfma_f32_16x16x32_bf16 v[16:19], v[84:87], v[228:231], v[16:19]
	v_mfma_f32_16x16x32_bf16 v[16:19], v[96:99], v[232:235], v[16:19]
	v_mfma_f32_16x16x32_bf16 v[12:15], v[140:143], v[228:231], v[12:15]
	v_mfma_f32_16x16x32_bf16 v[12:15], v[144:147], v[232:235], v[12:15]
	v_mfma_f32_16x16x32_bf16 v[56:59], v[152:155], v[186:189], v[56:59]
	v_mfma_f32_16x16x32_bf16 v[56:59], v[156:159], v[208:211], v[56:59]
	v_mfma_f32_16x16x32_bf16 v[52:55], v[160:163], v[186:189], v[52:55]
	v_mfma_f32_16x16x32_bf16 v[52:55], v[182:185], v[208:211], v[52:55]
	v_mfma_f32_16x16x32_bf16 v[40:43], v[152:155], v[212:215], v[40:43]
	v_mfma_f32_16x16x32_bf16 v[40:43], v[156:159], v[216:219], v[40:43]
	v_mfma_f32_16x16x32_bf16 v[36:39], v[160:163], v[212:215], v[36:39]
	v_mfma_f32_16x16x32_bf16 v[36:39], v[182:185], v[216:219], v[36:39]
	v_mfma_f32_16x16x32_bf16 v[24:27], v[152:155], v[220:223], v[24:27]
	v_mfma_f32_16x16x32_bf16 v[24:27], v[156:159], v[224:227], v[24:27]
	v_mfma_f32_16x16x32_bf16 v[20:23], v[160:163], v[220:223], v[20:23]
	v_mfma_f32_16x16x32_bf16 v[20:23], v[182:185], v[224:227], v[20:23]
	v_mfma_f32_16x16x32_bf16 v[8:11], v[152:155], v[228:231], v[8:11]
	v_mfma_f32_16x16x32_bf16 v[8:11], v[156:159], v[232:235], v[8:11]
	v_mfma_f32_16x16x32_bf16 v[2:5], v[160:163], v[228:231], v[4:7]
	s_setprio 3
	s_barrier
	v_mfma_f32_16x16x32_bf16 v[2:5], v[182:185], v[232:235], v[2:5]
	s_setprio 0
	s_add_i32 s96, 0, 0x18000
	v_add_u32_e32 v1, s96, v194
	v_xor_b32_e32 v253, 64, v1
	s_add_i32 s97, 0, 0x1c000
	ds_read_b128 v[84:87], v1
	ds_read_b128 v[96:99], v253
	ds_read_b128 v[140:143], v1 offset:2048
	ds_read_b128 v[144:147], v253 offset:2048
	v_add_u32_e32 v1, s97, v194
	v_xor_b32_e32 v253, 64, v1
	ds_read_b128 v[152:155], v1
	ds_read_b128 v[156:159], v253
	ds_read_b128 v[160:163], v1 offset:2048
	ds_read_b128 v[182:185], v253 offset:2048
	s_mov_b32 m0, s41
	ds_read_b128 v[224:227], v250 offset:36864
	global_load_lds_dwordx4 v164, s[8:9]
	s_mov_b32 m0, s68
	ds_read_b128 v[228:231], v198 offset:38912
	global_load_lds_dwordx4 v168, s[8:9]
	s_add_u32 s8, s8, 0x100000
	s_addc_u32 s9, s9, 0
	s_mov_b32 m0, s69
	ds_read_b128 v[186:189], v198 offset:32768
	ds_read_b128 v[208:211], v250 offset:32768
	ds_read_b128 v[212:215], v198 offset:34816
	ds_read_b128 v[216:219], v250 offset:34816
	ds_read_b128 v[220:223], v198 offset:36864
	global_load_lds_dwordx4 v164, s[8:9]
	s_mov_b32 m0, s70
	ds_read_b128 v[232:235], v250 offset:38912
	global_load_lds_dwordx4 v168, s[8:9]
	s_waitcnt vmcnt(8)
	s_waitcnt lgkmcnt(0)
	s_setprio 2
	s_barrier
; #define PG8_STAGE(bufoff, gbase, voff) do { _Pragma("unroll") for (int _i = 0; _i < 2; ++_i) \
;         __builtin_amdgcn_global_load_lds((const unsigned*)((const char*)(gbase) + (voff)[_i]), (LAS unsigned*)(lds + (bufoff) + ldsw + _i * 8192), 16, 0, 0); } while (0)
; #define PG8_LDA(dst, b, h) do { _Pragma("unroll") for (int m = 0; m < 4; ++m) _Pragma("unroll") for (int k = 0; k < 2; ++k) dst[m][k] = *(const LAS bf16x8*)(lds + PG8_SA(b, h) + aoff + m * 2048 + k * 1024); } while (0)
; #define PG8_MMA(ai, bj, At, Bt) do { __builtin_amdgcn_s_setprio(3); _Pragma("unroll") for (int m = 0; m < 4; ++m) _Pragma("unroll") for (int n = 0; n < 2; ++n) _Pragma("unroll") for (int k = 0; k < 2; ++k) \
;         acc[ai][bj][m][n] = __builtin_amdgcn_mfma_f32_16x16x32_bf16(Bt[n][k], At[m][k], acc[ai][bj][m][n], 0, 0, 0); __builtin_amdgcn_s_setprio(0); } while (0)
; #define PG8_WAIT_V(n) asm volatile("s_waitcnt vmcnt(" #n ")" ::: "memory")
; #define PG8_WAIT_L(n) asm volatile("s_waitcnt lgkmcnt(" #n ")" ::: "memory")
; #define PG8_BAR __builtin_amdgcn_s_barrier()
; #define PG8_SCHED __builtin_amdgcn_sched_barrier(0)
; template <class Epi, class Sched, bool ALIGN_EPI = false, bool SP2 = false>
; __device__ __forceinline__ void gemm_phase(LAS unsigned char* lds, const Gemm g, const Sched& S, const Epi& E) {
;     ...
;             PG8_WAIT_V(8); PG8_WAIT_L(0); PG8_BAR; PG8_MMA(0, 0, At, B0); PG8_MMA(0, 1, At, B1); PG8_BAR; PG8_SCHED;
;             PG8_LDA(At, 1, 1); PG8_STAGE(PG8_SB(1, 0), b3, voffB); PG8_STAGE(PG8_SB(1, 1), b3 + hsB, voffB); PG8_STAGE(PG8_SA(1, 0), a3, voffA);
;             PG8_WAIT_V(8); PG8_WAIT_L(0); PG8_BAR; PG8_MMA(1, 0, At, B0); PG8_MMA(1, 1, At, B1); PG8_BAR; PG8_SCHED;
	v_mfma_f32_16x16x32_bf16 v[136:139], v[84:87], v[186:189], v[136:139]
	v_mfma_f32_16x16x32_bf16 v[136:139], v[96:99], v[208:211], v[136:139]
	v_mfma_f32_16x16x32_bf16 v[132:135], v[140:143], v[186:189], v[132:135]
	v_mfma_f32_16x16x32_bf16 v[132:135], v[144:147], v[208:211], v[132:135]
	v_mfma_f32_16x16x32_bf16 v[120:123], v[84:87], v[212:215], v[120:123]
	v_mfma_f32_16x16x32_bf16 v[120:123], v[96:99], v[216:219], v[120:123]
	v_mfma_f32_16x16x32_bf16 v[116:119], v[140:143], v[212:215], v[116:119]
	v_mfma_f32_16x16x32_bf16 v[116:119], v[144:147], v[216:219], v[116:119]
	v_mfma_f32_16x16x32_bf16 v[104:107], v[84:87], v[220:223], v[104:107]
	v_mfma_f32_16x16x32_bf16 v[104:107], v[96:99], v[224:227], v[104:107]
	v_mfma_f32_16x16x32_bf16 v[100:103], v[140:143], v[220:223], v[100:103]
	v_mfma_f32_16x16x32_bf16 v[100:103], v[144:147], v[224:227], v[100:103]
	v_mfma_f32_16x16x32_bf16 v[80:83], v[84:87], v[228:231], v[80:83]
	v_mfma_f32_16x16x32_bf16 v[80:83], v[96:99], v[232:235], v[80:83]
	v_mfma_f32_16x16x32_bf16 v[76:79], v[140:143], v[228:231], v[76:79]
	v_mfma_f32_16x16x32_bf16 v[76:79], v[144:147], v[232:235], v[76:79]
	v_mfma_f32_16x16x32_bf16 v[128:131], v[152:155], v[186:189], v[128:131]
	v_mfma_f32_16x16x32_bf16 v[128:131], v[156:159], v[208:211], v[128:131]
	v_mfma_f32_16x16x32_bf16 v[124:127], v[160:163], v[186:189], v[124:127]
	v_mfma_f32_16x16x32_bf16 v[124:127], v[182:185], v[208:211], v[124:127]
	v_mfma_f32_16x16x32_bf16 v[112:115], v[152:155], v[212:215], v[112:115]
	v_mfma_f32_16x16x32_bf16 v[112:115], v[156:159], v[216:219], v[112:115]
	v_mfma_f32_16x16x32_bf16 v[108:111], v[160:163], v[212:215], v[108:111]
	v_mfma_f32_16x16x32_bf16 v[108:111], v[182:185], v[216:219], v[108:111]
	v_mfma_f32_16x16x32_bf16 v[92:95], v[152:155], v[220:223], v[92:95]
	v_mfma_f32_16x16x32_bf16 v[92:95], v[156:159], v[224:227], v[92:95]
	v_mfma_f32_16x16x32_bf16 v[88:91], v[160:163], v[220:223], v[88:91]
	v_mfma_f32_16x16x32_bf16 v[88:91], v[182:185], v[224:227], v[88:91]
	v_mfma_f32_16x16x32_bf16 v[72:75], v[152:155], v[228:231], v[72:75]
	v_mfma_f32_16x16x32_bf16 v[72:75], v[156:159], v[232:235], v[72:75]
	v_mfma_f32_16x16x32_bf16 v[68:71], v[160:163], v[228:231], v[68:71]
	s_setprio 3
	s_barrier
	v_mfma_f32_16x16x32_bf16 v[68:71], v[182:185], v[232:235], v[68:71]
	s_setprio 0
	s_add_i32 s8, s96, s31
	s_add_u32 s100, s4, s24
	s_addc_u32 s101, s5, s25
	s_mov_b32 m0, s8
	ds_read_b128 v[186:189], v198 offset:49152
	ds_read_b128 v[208:211], v250 offset:49152
	ds_read_b128 v[212:215], v198 offset:51200
	ds_read_b128 v[216:219], v250 offset:51200
	ds_read_b128 v[220:223], v198 offset:53248
	ds_read_b128 v[224:227], v250 offset:53248
	global_load_lds_dwordx4 v166, s[100:101]
	s_add_i32 m0, s8, 0x2000
	s_add_u32 s4, s4, 0x104080
	s_addc_u32 s5, s5, 0
	s_add_i32 s8, s97, s31
	global_load_lds_dwordx4 v170, s[100:101]
	s_mov_b32 m0, s8
	ds_read_b128 v[228:231], v198 offset:55296
	global_load_lds_dwordx4 v166, s[4:5]
	s_add_i32 m0, s8, 0x2000
	ds_read_b128 v[232:235], v250 offset:55296
	global_load_lds_dwordx4 v170, s[4:5]
	s_waitcnt vmcnt(6)
	s_waitcnt lgkmcnt(0)
	s_setprio 2
	s_barrier
	v_mfma_f32_16x16x32_bf16 v[64:67], v[84:87], v[186:189], v[64:67]
	v_mfma_f32_16x16x32_bf16 v[64:67], v[96:99], v[208:211], v[64:67]
	v_mfma_f32_16x16x32_bf16 v[60:63], v[140:143], v[186:189], v[60:63]
	v_mfma_f32_16x16x32_bf16 v[60:63], v[144:147], v[208:211], v[60:63]
	v_mfma_f32_16x16x32_bf16 v[48:51], v[84:87], v[212:215], v[48:51]
	v_mfma_f32_16x16x32_bf16 v[48:51], v[96:99], v[216:219], v[48:51]
	v_mfma_f32_16x16x32_bf16 v[44:47], v[140:143], v[212:215], v[44:47]
	v_mfma_f32_16x16x32_bf16 v[44:47], v[144:147], v[216:219], v[44:47]
	v_mfma_f32_16x16x32_bf16 v[32:35], v[84:87], v[220:223], v[32:35]
	v_mfma_f32_16x16x32_bf16 v[32:35], v[96:99], v[224:227], v[32:35]
	v_mfma_f32_16x16x32_bf16 v[28:31], v[140:143], v[220:223], v[28:31]
	v_mfma_f32_16x16x32_bf16 v[28:31], v[144:147], v[224:227], v[28:31]
	v_mfma_f32_16x16x32_bf16 v[16:19], v[84:87], v[228:231], v[16:19]
	v_mfma_f32_16x16x32_bf16 v[16:19], v[96:99], v[232:235], v[16:19]
	v_mfma_f32_16x16x32_bf16 v[12:15], v[140:143], v[228:231], v[12:15]
	v_mfma_f32_16x16x32_bf16 v[12:15], v[144:147], v[232:235], v[12:15]
	v_mfma_f32_16x16x32_bf16 v[56:59], v[152:155], v[186:189], v[56:59]
	v_mfma_f32_16x16x32_bf16 v[56:59], v[156:159], v[208:211], v[56:59]
	v_mfma_f32_16x16x32_bf16 v[52:55], v[160:163], v[186:189], v[52:55]
	v_mfma_f32_16x16x32_bf16 v[52:55], v[182:185], v[208:211], v[52:55]
	v_mfma_f32_16x16x32_bf16 v[40:43], v[152:155], v[212:215], v[40:43]
	v_mfma_f32_16x16x32_bf16 v[40:43], v[156:159], v[216:219], v[40:43]
	v_mfma_f32_16x16x32_bf16 v[36:39], v[160:163], v[212:215], v[36:39]
	v_mfma_f32_16x16x32_bf16 v[36:39], v[182:185], v[216:219], v[36:39]
	v_mfma_f32_16x16x32_bf16 v[24:27], v[152:155], v[220:223], v[24:27]
	v_mfma_f32_16x16x32_bf16 v[24:27], v[156:159], v[224:227], v[24:27]
	v_mfma_f32_16x16x32_bf16 v[20:23], v[160:163], v[220:223], v[20:23]
	v_mfma_f32_16x16x32_bf16 v[20:23], v[182:185], v[224:227], v[20:23]
	v_mfma_f32_16x16x32_bf16 v[6:9], v[152:155], v[228:231], v[8:11]
	v_mfma_f32_16x16x32_bf16 v[8:11], v[156:159], v[232:235], v[6:9]
	v_mfma_f32_16x16x32_bf16 v[2:5], v[160:163], v[228:231], v[2:5]
	s_setprio 3
	s_barrier
	v_mfma_f32_16x16x32_bf16 v[4:7], v[182:185], v[232:235], v[2:5]
	s_setprio 0
	s_add_i32 s95, s95, 2
	s_add_u32 s66, s66, 0x100
	s_addc_u32 s67, s67, 0
	s_cmp_gt_u32 s95, 61
	s_cbranch_scc1 .LBB0_237

; #define PG8_STAGE(bufoff, gbase, voff) do { _Pragma("unroll") for (int _i = 0; _i < 2; ++_i) \
;         __builtin_amdgcn_global_load_lds((const unsigned*)((const char*)(gbase) + (voff)[_i]), (LAS unsigned*)(lds + (bufoff) + ldsw + _i * 8192), 16, 0, 0); } while (0)
; #define PG8_LDA(dst, b, h) do { _Pragma("unroll") for (int m = 0; m < 4; ++m) _Pragma("unroll") for (int k = 0; k < 2; ++k) dst[m][k] = *(const LAS bf16x8*)(lds + PG8_SA(b, h) + aoff + m * 2048 + k * 1024); } while (0)
; #define PG8_LDB(dst, b, h) do { _Pragma("unroll") for (int n = 0; n < 2; ++n) _Pragma("unroll") for (int k = 0; k < 2; ++k) dst[n][k] = *(const LAS bf16x8*)(lds + PG8_SB(b, h) + boff + n * 2048 + k * 1024); } while (0)
; #define PG8_MMA(ai, bj, At, Bt) do { __builtin_amdgcn_s_setprio(3); _Pragma("unroll") for (int m = 0; m < 4; ++m) _Pragma("unroll") for (int n = 0; n < 2; ++n) _Pragma("unroll") for (int k = 0; k < 2; ++k) \
;         acc[ai][bj][m][n] = __builtin_amdgcn_mfma_f32_16x16x32_bf16(Bt[n][k], At[m][k], acc[ai][bj][m][n], 0, 0, 0); __builtin_amdgcn_s_setprio(0); } while (0)
; #define PG8_WAIT_V(n) asm volatile("s_waitcnt vmcnt(" #n ")" ::: "memory")
; #define PG8_WAIT_L(n) asm volatile("s_waitcnt lgkmcnt(" #n ")" ::: "memory")
; #define PG8_BAR __builtin_amdgcn_s_barrier()
; #define PG8_SCHED __builtin_amdgcn_sched_barrier(0)
; template <class Epi, class Sched, bool ALIGN_EPI = false, bool SP2 = false>
; __device__ __forceinline__ void gemm_phase(LAS unsigned char* lds, const Gemm g, const Sched& S, const Epi& E) {
;     ...
;             PG8_LDB(B0, 0, 0); PG8_LDB(B1, 0, 1); PG8_SCHED; PG8_LDA(At, 0, 0); PG8_STAGE(PG8_SA(1, 1), a1 + hsA, voffA);
;             PG8_WAIT_V(8); PG8_WAIT_L(0); PG8_BAR; PG8_MMA(0, 0, At, B0); PG8_MMA(0, 1, At, B1); PG8_BAR; PG8_SCHED;
;             PG8_LDA(At, 0, 1); PG8_STAGE(PG8_SB(0, 0), b2, voffB); PG8_STAGE(PG8_SB(0, 1), b2 + hsB, voffB); PG8_STAGE(PG8_SA(0, 0), a2, voffA);
;             PG8_WAIT_V(8); PG8_WAIT_L(0); PG8_BAR; PG8_MMA(1, 0, At, B0); PG8_MMA(1, 1, At, B1); PG8_BAR; PG8_SCHED;
.LBB0_309:
	ds_read_b128 v[112:115], v175
	ds_read_b128 v[132:135], v251
	ds_read_b128 v[136:139], v175 offset:2048
	ds_read_b128 v[140:143], v251 offset:2048
	ds_read_b128 v[144:147], v176
	ds_read_b128 v[148:151], v252
	ds_read_b128 v[184:187], v176 offset:2048
	ds_read_b128 v[188:191], v252 offset:2048
	s_add_u32 s24, s4, 0xffefc080
	s_addc_u32 s25, s5, -1
	s_cmp_eq_u32 s73, 60
	s_cselect_b32 s27, s11, s25
	s_cselect_b32 s26, s10, s24
	s_cselect_b32 s25, s21, s72
	s_cselect_b32 s24, s20, s71
	s_sub_u32 s100, s4, 0x104000
	s_subb_u32 s101, s5, 0
	s_mov_b32 m0, s42
	ds_read_b128 v[218:221], v250 offset:4096
	global_load_lds_dwordx4 v152, s[100:101]
	s_mov_b32 m0, s43
	ds_read_b128 v[222:225], v177 offset:6144
	global_load_lds_dwordx4 v156, s[100:101]
	s_add_i32 m0, s36, 0xc000
	ds_read_b128 v[192:195], v177
	ds_read_b128 v[196:199], v250
	ds_read_b128 v[206:209], v177 offset:2048
	ds_read_b128 v[210:213], v250 offset:2048
	ds_read_b128 v[214:217], v177 offset:4096
	global_load_lds_dwordx4 v164, s[4:5]
	s_add_i32 m0, s36, 0xe000
	ds_read_b128 v[226:229], v250 offset:6144
	global_load_lds_dwordx4 v166, s[4:5]
	s_waitcnt vmcnt(8)
	s_waitcnt lgkmcnt(0)
	s_setprio 2
	s_barrier
	v_mfma_f32_16x16x32_bf16 v[128:131], v[112:115], v[192:195], v[128:131]
	v_mfma_f32_16x16x32_bf16 v[128:131], v[132:135], v[196:199], v[128:131]
	v_mfma_f32_16x16x32_bf16 v[124:127], v[136:139], v[192:195], v[124:127]
	v_mfma_f32_16x16x32_bf16 v[124:127], v[140:143], v[196:199], v[124:127]
	v_mfma_f32_16x16x32_bf16 v[108:111], v[112:115], v[206:209], v[108:111]
	v_mfma_f32_16x16x32_bf16 v[108:111], v[132:135], v[210:213], v[108:111]
	v_mfma_f32_16x16x32_bf16 v[104:107], v[136:139], v[206:209], v[104:107]
	v_mfma_f32_16x16x32_bf16 v[104:107], v[140:143], v[210:213], v[104:107]
	v_mfma_f32_16x16x32_bf16 v[92:95], v[112:115], v[214:217], v[92:95]
	v_mfma_f32_16x16x32_bf16 v[92:95], v[132:135], v[218:221], v[92:95]
	v_mfma_f32_16x16x32_bf16 v[88:91], v[136:139], v[214:217], v[88:91]
	v_mfma_f32_16x16x32_bf16 v[88:91], v[140:143], v[218:221], v[88:91]
	v_mfma_f32_16x16x32_bf16 v[76:79], v[112:115], v[222:225], v[76:79]
	v_mfma_f32_16x16x32_bf16 v[76:79], v[132:135], v[226:229], v[76:79]
	v_mfma_f32_16x16x32_bf16 v[72:75], v[136:139], v[222:225], v[72:75]
	v_mfma_f32_16x16x32_bf16 v[72:75], v[140:143], v[226:229], v[72:75]
	v_mfma_f32_16x16x32_bf16 v[120:123], v[144:147], v[192:195], v[120:123]
	v_mfma_f32_16x16x32_bf16 v[120:123], v[148:151], v[196:199], v[120:123]
	v_mfma_f32_16x16x32_bf16 v[116:119], v[184:187], v[192:195], v[116:119]
	v_mfma_f32_16x16x32_bf16 v[116:119], v[188:191], v[196:199], v[116:119]
	v_mfma_f32_16x16x32_bf16 v[100:103], v[144:147], v[206:209], v[100:103]
	v_mfma_f32_16x16x32_bf16 v[100:103], v[148:151], v[210:213], v[100:103]
	v_mfma_f32_16x16x32_bf16 v[96:99], v[184:187], v[206:209], v[96:99]
	v_mfma_f32_16x16x32_bf16 v[96:99], v[188:191], v[210:213], v[96:99]
	v_mfma_f32_16x16x32_bf16 v[84:87], v[144:147], v[214:217], v[84:87]
	v_mfma_f32_16x16x32_bf16 v[84:87], v[148:151], v[218:221], v[84:87]
	v_mfma_f32_16x16x32_bf16 v[80:83], v[184:187], v[214:217], v[80:83]
	v_mfma_f32_16x16x32_bf16 v[80:83], v[188:191], v[218:221], v[80:83]
	v_mfma_f32_16x16x32_bf16 v[68:71], v[144:147], v[222:225], v[68:71]
	v_mfma_f32_16x16x32_bf16 v[68:71], v[148:151], v[226:229], v[68:71]
	v_mfma_f32_16x16x32_bf16 v[64:67], v[184:187], v[222:225], v[64:67]
	s_setprio 3
	s_barrier
	v_mfma_f32_16x16x32_bf16 v[64:67], v[188:191], v[226:229], v[64:67]
	s_setprio 0
	s_add_i32 s74, s45, s31
	s_mov_b32 m0, s74
	ds_read_b128 v[192:195], v177 offset:16384
	ds_read_b128 v[196:199], v250 offset:16384
	ds_read_b128 v[206:209], v177 offset:18432
	ds_read_b128 v[210:213], v250 offset:18432
	ds_read_b128 v[214:217], v177 offset:20480
	ds_read_b128 v[218:221], v250 offset:20480
	global_load_lds_dwordx4 v154, s[24:25]
	s_add_i32 m0, s74, 0x2000
	s_add_u32 s74, s24, 0x41000
	s_addc_u32 s75, s25, 0
	s_add_i32 s78, s46, s31
	global_load_lds_dwordx4 v158, s[24:25]
	s_mov_b32 m0, s78
	ds_read_b128 v[222:225], v177 offset:22528
	global_load_lds_dwordx4 v154, s[74:75]
	s_add_i32 m0, s78, 0x2000
	ds_read_b128 v[226:229], v250 offset:22528
	global_load_lds_dwordx4 v158, s[74:75]
	s_waitcnt vmcnt(6)
	s_waitcnt lgkmcnt(0)
	s_setprio 2
	s_barrier
	v_mfma_f32_16x16x32_bf16 v[60:63], v[112:115], v[192:195], v[60:63]
	v_mfma_f32_16x16x32_bf16 v[60:63], v[132:135], v[196:199], v[60:63]
	v_mfma_f32_16x16x32_bf16 v[56:59], v[136:139], v[192:195], v[56:59]
	v_mfma_f32_16x16x32_bf16 v[56:59], v[140:143], v[196:199], v[56:59]
	v_mfma_f32_16x16x32_bf16 v[44:47], v[112:115], v[206:209], v[44:47]
	v_mfma_f32_16x16x32_bf16 v[44:47], v[132:135], v[210:213], v[44:47]
	v_mfma_f32_16x16x32_bf16 v[40:43], v[136:139], v[206:209], v[40:43]
	v_mfma_f32_16x16x32_bf16 v[40:43], v[140:143], v[210:213], v[40:43]
	v_mfma_f32_16x16x32_bf16 v[28:31], v[112:115], v[214:217], v[28:31]
	v_mfma_f32_16x16x32_bf16 v[28:31], v[132:135], v[218:221], v[28:31]
	v_mfma_f32_16x16x32_bf16 v[24:27], v[136:139], v[214:217], v[24:27]
	v_mfma_f32_16x16x32_bf16 v[24:27], v[140:143], v[218:221], v[24:27]
	v_mfma_f32_16x16x32_bf16 v[12:15], v[112:115], v[222:225], v[12:15]
	v_mfma_f32_16x16x32_bf16 v[12:15], v[132:135], v[226:229], v[12:15]
	v_mfma_f32_16x16x32_bf16 v[8:11], v[136:139], v[222:225], v[8:11]
	v_mfma_f32_16x16x32_bf16 v[8:11], v[140:143], v[226:229], v[8:11]
	v_mfma_f32_16x16x32_bf16 v[52:55], v[144:147], v[192:195], v[52:55]
	v_mfma_f32_16x16x32_bf16 v[52:55], v[148:151], v[196:199], v[52:55]
	v_mfma_f32_16x16x32_bf16 v[48:51], v[184:187], v[192:195], v[48:51]
	v_mfma_f32_16x16x32_bf16 v[48:51], v[188:191], v[196:199], v[48:51]
	v_mfma_f32_16x16x32_bf16 v[36:39], v[144:147], v[206:209], v[36:39]
	v_mfma_f32_16x16x32_bf16 v[36:39], v[148:151], v[210:213], v[36:39]
	v_mfma_f32_16x16x32_bf16 v[32:35], v[184:187], v[206:209], v[32:35]
	v_mfma_f32_16x16x32_bf16 v[32:35], v[188:191], v[210:213], v[32:35]
	v_mfma_f32_16x16x32_bf16 v[20:23], v[144:147], v[214:217], v[20:23]
	v_mfma_f32_16x16x32_bf16 v[20:23], v[148:151], v[218:221], v[20:23]
	v_mfma_f32_16x16x32_bf16 v[16:19], v[184:187], v[214:217], v[16:19]
	v_mfma_f32_16x16x32_bf16 v[16:19], v[188:191], v[218:221], v[16:19]
	v_mfma_f32_16x16x32_bf16 v[4:7], v[144:147], v[222:225], v[4:7]
	v_mfma_f32_16x16x32_bf16 v[4:7], v[148:151], v[226:229], v[4:7]
	v_mfma_f32_16x16x32_bf16 v[0:3], v[184:187], v[222:225], v[0:3]
	s_setprio 3
	s_barrier
; #define PG8_STAGE(bufoff, gbase, voff) do { _Pragma("unroll") for (int _i = 0; _i < 2; ++_i) \
;         __builtin_amdgcn_global_load_lds((const unsigned*)((const char*)(gbase) + (voff)[_i]), (LAS unsigned*)(lds + (bufoff) + ldsw + _i * 8192), 16, 0, 0); } while (0)
; #define PG8_LDA(dst, b, h) do { _Pragma("unroll") for (int m = 0; m < 4; ++m) _Pragma("unroll") for (int k = 0; k < 2; ++k) dst[m][k] = *(const LAS bf16x8*)(lds + PG8_SA(b, h) + aoff + m * 2048 + k * 1024); } while (0)
; #define PG8_LDB(dst, b, h) do { _Pragma("unroll") for (int n = 0; n < 2; ++n) _Pragma("unroll") for (int k = 0; k < 2; ++k) dst[n][k] = *(const LAS bf16x8*)(lds + PG8_SB(b, h) + boff + n * 2048 + k * 1024); } while (0)
; #define PG8_MMA(ai, bj, At, Bt) do { __builtin_amdgcn_s_setprio(3); _Pragma("unroll") for (int m = 0; m < 4; ++m) _Pragma("unroll") for (int n = 0; n < 2; ++n) _Pragma("unroll") for (int k = 0; k < 2; ++k) \
;         acc[ai][bj][m][n] = __builtin_amdgcn_mfma_f32_16x16x32_bf16(Bt[n][k], At[m][k], acc[ai][bj][m][n], 0, 0, 0); __builtin_amdgcn_s_setprio(0); } while (0)
; #define PG8_WAIT_V(n) asm volatile("s_waitcnt vmcnt(" #n ")" ::: "memory")
; #define PG8_WAIT_L(n) asm volatile("s_waitcnt lgkmcnt(" #n ")" ::: "memory")
; #define PG8_BAR __builtin_amdgcn_s_barrier()
; #define PG8_SCHED __builtin_amdgcn_sched_barrier(0)
; template <class Epi, class Sched, bool ALIGN_EPI = false, bool SP2 = false>
; __device__ __forceinline__ void gemm_phase(LAS unsigned char* lds, const Gemm g, const Sched& S, const Epi& E) {
;     ...
;             PG8_LDB(B0, 1, 0); PG8_LDB(B1, 1, 1); PG8_SCHED; PG8_LDA(At, 1, 0); PG8_STAGE(PG8_SA(0, 1), a2 + hsA, voffA);
;             PG8_WAIT_V(8); PG8_WAIT_L(0); PG8_BAR; PG8_MMA(0, 0, At, B0); PG8_MMA(0, 1, At, B1); PG8_BAR; PG8_SCHED;
;             PG8_LDA(At, 1, 1); PG8_STAGE(PG8_SB(1, 0), b3, voffB); PG8_STAGE(PG8_SB(1, 1), b3 + hsB, voffB); PG8_STAGE(PG8_SA(1, 0), a3, voffA);
;             PG8_WAIT_V(8); PG8_WAIT_L(0); PG8_BAR; PG8_MMA(1, 0, At, B0); PG8_MMA(1, 1, At, B1); PG8_BAR; PG8_SCHED;
	v_mfma_f32_16x16x32_bf16 v[0:3], v[188:191], v[226:229], v[0:3]
	s_setprio 0
	s_add_i32 s74, 0, 0x18000
	s_add_i32 s75, 0, 0x1c000
	ds_read_b128 v[112:115], v246
	ds_read_b128 v[132:135], v247
	ds_read_b128 v[136:139], v246 offset:2048
	ds_read_b128 v[140:143], v247 offset:2048
	ds_read_b128 v[144:147], v248
	ds_read_b128 v[148:151], v249
	ds_read_b128 v[184:187], v248 offset:2048
	ds_read_b128 v[188:191], v249 offset:2048
	s_mov_b32 m0, s36
	ds_read_b128 v[218:221], v250 offset:36864
	global_load_lds_dwordx4 v152, s[26:27]
	s_mov_b32 m0, s37
	ds_read_b128 v[222:225], v177 offset:38912
	global_load_lds_dwordx4 v156, s[26:27]
	s_add_u32 s26, s26, 0x104000
	s_addc_u32 s27, s27, 0
	s_mov_b32 m0, s38
	ds_read_b128 v[192:195], v177 offset:32768
	ds_read_b128 v[196:199], v250 offset:32768
	ds_read_b128 v[206:209], v177 offset:34816
	ds_read_b128 v[210:213], v250 offset:34816
	ds_read_b128 v[214:217], v177 offset:36864
	global_load_lds_dwordx4 v152, s[26:27]
	s_mov_b32 m0, s39
	ds_read_b128 v[226:229], v250 offset:38912
	global_load_lds_dwordx4 v156, s[26:27]
	s_waitcnt vmcnt(8)
	s_waitcnt lgkmcnt(0)
	s_setprio 2
	s_barrier
	v_mfma_f32_16x16x32_bf16 v[128:131], v[112:115], v[192:195], v[128:131]
	v_mfma_f32_16x16x32_bf16 v[128:131], v[132:135], v[196:199], v[128:131]
	v_mfma_f32_16x16x32_bf16 v[124:127], v[136:139], v[192:195], v[124:127]
	v_mfma_f32_16x16x32_bf16 v[124:127], v[140:143], v[196:199], v[124:127]
	v_mfma_f32_16x16x32_bf16 v[108:111], v[112:115], v[206:209], v[108:111]
	v_mfma_f32_16x16x32_bf16 v[108:111], v[132:135], v[210:213], v[108:111]
	v_mfma_f32_16x16x32_bf16 v[104:107], v[136:139], v[206:209], v[104:107]
	v_mfma_f32_16x16x32_bf16 v[104:107], v[140:143], v[210:213], v[104:107]
	v_mfma_f32_16x16x32_bf16 v[92:95], v[112:115], v[214:217], v[92:95]
	v_mfma_f32_16x16x32_bf16 v[92:95], v[132:135], v[218:221], v[92:95]
	v_mfma_f32_16x16x32_bf16 v[88:91], v[136:139], v[214:217], v[88:91]
	v_mfma_f32_16x16x32_bf16 v[88:91], v[140:143], v[218:221], v[88:91]
	v_mfma_f32_16x16x32_bf16 v[76:79], v[112:115], v[222:225], v[76:79]
	v_mfma_f32_16x16x32_bf16 v[76:79], v[132:135], v[226:229], v[76:79]
	v_mfma_f32_16x16x32_bf16 v[72:75], v[136:139], v[222:225], v[72:75]
	v_mfma_f32_16x16x32_bf16 v[72:75], v[140:143], v[226:229], v[72:75]
	v_mfma_f32_16x16x32_bf16 v[120:123], v[144:147], v[192:195], v[120:123]
	v_mfma_f32_16x16x32_bf16 v[120:123], v[148:151], v[196:199], v[120:123]
	v_mfma_f32_16x16x32_bf16 v[116:119], v[184:187], v[192:195], v[116:119]
	v_mfma_f32_16x16x32_bf16 v[116:119], v[188:191], v[196:199], v[116:119]
	v_mfma_f32_16x16x32_bf16 v[100:103], v[144:147], v[206:209], v[100:103]
	v_mfma_f32_16x16x32_bf16 v[100:103], v[148:151], v[210:213], v[100:103]
	v_mfma_f32_16x16x32_bf16 v[96:99], v[184:187], v[206:209], v[96:99]
	v_mfma_f32_16x16x32_bf16 v[96:99], v[188:191], v[210:213], v[96:99]
	v_mfma_f32_16x16x32_bf16 v[84:87], v[144:147], v[214:217], v[84:87]
	v_mfma_f32_16x16x32_bf16 v[84:87], v[148:151], v[218:221], v[84:87]
	v_mfma_f32_16x16x32_bf16 v[80:83], v[184:187], v[214:217], v[80:83]
	v_mfma_f32_16x16x32_bf16 v[80:83], v[188:191], v[218:221], v[80:83]
	v_mfma_f32_16x16x32_bf16 v[68:71], v[144:147], v[222:225], v[68:71]
	v_mfma_f32_16x16x32_bf16 v[68:71], v[148:151], v[226:229], v[68:71]
	v_mfma_f32_16x16x32_bf16 v[64:67], v[184:187], v[222:225], v[64:67]
	s_setprio 3
	s_barrier
	v_mfma_f32_16x16x32_bf16 v[64:67], v[188:191], v[226:229], v[64:67]
	s_setprio 0
	s_add_i32 s26, s74, s31
	s_add_u32 s100, s24, s14
	s_addc_u32 s101, s25, s15
	s_mov_b32 m0, s26
	ds_read_b128 v[192:195], v177 offset:49152
	ds_read_b128 v[196:199], v250 offset:49152
	ds_read_b128 v[206:209], v177 offset:51200
	ds_read_b128 v[210:213], v250 offset:51200
	ds_read_b128 v[214:217], v177 offset:53248
	ds_read_b128 v[218:221], v250 offset:53248
	global_load_lds_dwordx4 v154, s[100:101]
	s_add_i32 m0, s26, 0x2000
	s_add_u32 s24, s24, 0x41080
	s_addc_u32 s25, s25, 0
	s_add_i32 s26, s75, s31
	global_load_lds_dwordx4 v158, s[100:101]
	s_mov_b32 m0, s26
	ds_read_b128 v[222:225], v177 offset:55296
	global_load_lds_dwordx4 v154, s[24:25]
	s_add_i32 m0, s26, 0x2000
	ds_read_b128 v[226:229], v250 offset:55296
	global_load_lds_dwordx4 v158, s[24:25]
	s_waitcnt vmcnt(6)
	s_waitcnt lgkmcnt(0)
	s_setprio 2
	s_barrier
	v_mfma_f32_16x16x32_bf16 v[60:63], v[112:115], v[192:195], v[60:63]
	v_mfma_f32_16x16x32_bf16 v[60:63], v[132:135], v[196:199], v[60:63]
	v_mfma_f32_16x16x32_bf16 v[56:59], v[136:139], v[192:195], v[56:59]
	v_mfma_f32_16x16x32_bf16 v[56:59], v[140:143], v[196:199], v[56:59]
	v_mfma_f32_16x16x32_bf16 v[44:47], v[112:115], v[206:209], v[44:47]
	v_mfma_f32_16x16x32_bf16 v[44:47], v[132:135], v[210:213], v[44:47]
	v_mfma_f32_16x16x32_bf16 v[40:43], v[136:139], v[206:209], v[40:43]
	v_mfma_f32_16x16x32_bf16 v[40:43], v[140:143], v[210:213], v[40:43]
	v_mfma_f32_16x16x32_bf16 v[28:31], v[112:115], v[214:217], v[28:31]
	v_mfma_f32_16x16x32_bf16 v[28:31], v[132:135], v[218:221], v[28:31]
	v_mfma_f32_16x16x32_bf16 v[24:27], v[136:139], v[214:217], v[24:27]
	v_mfma_f32_16x16x32_bf16 v[24:27], v[140:143], v[218:221], v[24:27]
	v_mfma_f32_16x16x32_bf16 v[12:15], v[112:115], v[222:225], v[12:15]
	v_mfma_f32_16x16x32_bf16 v[12:15], v[132:135], v[226:229], v[12:15]
	v_mfma_f32_16x16x32_bf16 v[8:11], v[136:139], v[222:225], v[8:11]
	v_mfma_f32_16x16x32_bf16 v[8:11], v[140:143], v[226:229], v[8:11]
	v_mfma_f32_16x16x32_bf16 v[52:55], v[144:147], v[192:195], v[52:55]
	v_mfma_f32_16x16x32_bf16 v[52:55], v[148:151], v[196:199], v[52:55]
	v_mfma_f32_16x16x32_bf16 v[48:51], v[184:187], v[192:195], v[48:51]
	v_mfma_f32_16x16x32_bf16 v[48:51], v[188:191], v[196:199], v[48:51]
	v_mfma_f32_16x16x32_bf16 v[36:39], v[144:147], v[206:209], v[36:39]
	v_mfma_f32_16x16x32_bf16 v[36:39], v[148:151], v[210:213], v[36:39]
	v_mfma_f32_16x16x32_bf16 v[32:35], v[184:187], v[206:209], v[32:35]
	v_mfma_f32_16x16x32_bf16 v[32:35], v[188:191], v[210:213], v[32:35]
	v_mfma_f32_16x16x32_bf16 v[20:23], v[144:147], v[214:217], v[20:23]
	v_mfma_f32_16x16x32_bf16 v[20:23], v[148:151], v[218:221], v[20:23]
	v_mfma_f32_16x16x32_bf16 v[16:19], v[184:187], v[214:217], v[16:19]
	v_mfma_f32_16x16x32_bf16 v[16:19], v[188:191], v[218:221], v[16:19]
	v_mfma_f32_16x16x32_bf16 v[4:7], v[144:147], v[222:225], v[4:7]
	v_mfma_f32_16x16x32_bf16 v[4:7], v[148:151], v[226:229], v[4:7]
	v_mfma_f32_16x16x32_bf16 v[0:3], v[184:187], v[222:225], v[0:3]
	s_setprio 3
	s_barrier
	v_mfma_f32_16x16x32_bf16 v[0:3], v[188:191], v[226:229], v[0:3]
	s_setprio 0
	s_add_i32 s73, s73, 2
	s_add_u32 s4, s4, 0x100
	s_addc_u32 s5, s5, 0
	s_add_u32 s71, s71, 0x100
	s_addc_u32 s72, s72, 0
	s_cmp_gt_u32 s73, 61
	s_cbranch_scc0 .LBB0_309
	s_and_b64 vcc, exec, s[16:17]
	s_cbranch_vccz .LBB0_312
	s_barrier

; #define PG8_STAGE(bufoff, gbase, voff) do { _Pragma("unroll") for (int _i = 0; _i < 2; ++_i) \
;         __builtin_amdgcn_global_load_lds((const unsigned*)((const char*)(gbase) + (voff)[_i]), (LAS unsigned*)(lds + (bufoff) + ldsw + _i * 8192), 16, 0, 0); } while (0)
; #define PG8_LDA(dst, b, h) do { _Pragma("unroll") for (int m = 0; m < 4; ++m) _Pragma("unroll") for (int k = 0; k < 2; ++k) dst[m][k] = *(const LAS bf16x8*)(lds + PG8_SA(b, h) + aoff + m * 2048 + k * 1024); } while (0)
; #define PG8_LDB(dst, b, h) do { _Pragma("unroll") for (int n = 0; n < 2; ++n) _Pragma("unroll") for (int k = 0; k < 2; ++k) dst[n][k] = *(const LAS bf16x8*)(lds + PG8_SB(b, h) + boff + n * 2048 + k * 1024); } while (0)
; #define PG8_MMA(ai, bj, At, Bt) do { __builtin_amdgcn_s_setprio(3); _Pragma("unroll") for (int m = 0; m < 4; ++m) _Pragma("unroll") for (int n = 0; n < 2; ++n) _Pragma("unroll") for (int k = 0; k < 2; ++k) \
;         acc[ai][bj][m][n] = __builtin_amdgcn_mfma_f32_16x16x32_bf16(Bt[n][k], At[m][k], acc[ai][bj][m][n], 0, 0, 0); __builtin_amdgcn_s_setprio(0); } while (0)
; #define PG8_WAIT_V(n) asm volatile("s_waitcnt vmcnt(" #n ")" ::: "memory")
; template <class Epi, class Sched, bool ALIGN_EPI = false, bool SP2 = false>
; __device__ __forceinline__ void gemm_phase(LAS unsigned char* lds, const Gemm g, const Sched& S, const Epi& E) {
;     ...
;         for (int t = 0; t < nt; t += 2) {
;             const bool last = (t == nt - 2);
;             const char* a1 = cA + (size_t)(t + 1) * kstep;
;             const char* a2 = last ? nA : cA + (size_t)(t + 2) * kstep; const char* b2 = last ? nB : cB + (size_t)(t + 2) * kstep;
;             const char* a3 = a2 + kstep; const char* b3 = b2 + kstep;
;             if (last && has_next) S.a_ready(nxt);
;             if constexpr (Epi::MID) { if (t == nt / 2) E.mid(acc, cur, wr, wc, fr, fq); }
;             if constexpr (SP2) {
;             PG8_LDB(B0, 0, 0); PG8_LDB(B1, 0, 1); PG8_SCHED; PG8_LDA(At, 0, 0); PG8_STAGE(PG8_SA(1, 1), a1 + hsA, voffA);
;             PG8_WAIT_V(8); PG8_WAIT_L(0); PG8_BAR; PG8_MMA(0, 0, At, B0); PG8_MMA(0, 1, At, B1); PG8_BAR; PG8_SCHED;
;             PG8_LDA(At, 0, 1); PG8_STAGE(PG8_SB(0, 0), b2, voffB); PG8_STAGE(PG8_SB(0, 1), b2 + hsB, voffB); PG8_STAGE(PG8_SA(0, 0), a2, voffA);
;             PG8_WAIT_V(8); PG8_WAIT_L(0); PG8_BAR; PG8_MMA(1, 0, At, B0); PG8_MMA(1, 1, At, B1); PG8_BAR; PG8_SCHED;
.LBB0_350:
	ds_read_b128 v[140:143], v149
	ds_read_b128 v[156:159], v251
	ds_read_b128 v[160:163], v149 offset:2048
	ds_read_b128 v[164:167], v251 offset:2048
	ds_read_b128 v[168:171], v150
	ds_read_b128 v[172:175], v252
	ds_read_b128 v[176:179], v150 offset:2048
	ds_read_b128 v[180:183], v252 offset:2048
	s_add_u32 s16, s14, 0xffbfc080
	s_addc_u32 s17, s15, -1
	s_cmpk_eq_i32 s50, 0xfc
	s_cselect_b32 s21, s5, s17
	s_cselect_b32 s20, s4, s16
	s_cselect_b32 s17, s13, s49
	s_cselect_b32 s16, s12, s48
	s_sub_u32 s100, s14, 0x404000
	s_subb_u32 s101, s15, 0
	s_mov_b32 m0, s33
	ds_read_b128 v[204:207], v250 offset:4096
	global_load_lds_dwordx4 v128, s[100:101]
	s_mov_b32 m0, s38
	ds_read_b128 v[208:211], v151 offset:6144
	global_load_lds_dwordx4 v130, s[100:101]
	s_add_i32 m0, s26, 0xc000
	ds_read_b128 v[184:187], v151
	ds_read_b128 v[188:191], v250
	ds_read_b128 v[192:195], v151 offset:2048
	ds_read_b128 v[196:199], v250 offset:2048
	ds_read_b128 v[200:203], v151 offset:4096
	global_load_lds_dwordx4 v132, s[14:15]
	s_add_i32 m0, s26, 0xe000
	ds_read_b128 v[212:215], v250 offset:6144
	global_load_lds_dwordx4 v134, s[14:15]
	s_waitcnt vmcnt(8)
	s_waitcnt lgkmcnt(0)
	s_setprio 2
	s_barrier
	v_mfma_f32_16x16x32_bf16 v[124:127], v[140:143], v[184:187], v[124:127]
	v_mfma_f32_16x16x32_bf16 v[124:127], v[156:159], v[188:191], v[124:127]
	v_mfma_f32_16x16x32_bf16 v[120:123], v[160:163], v[184:187], v[120:123]
	v_mfma_f32_16x16x32_bf16 v[120:123], v[164:167], v[188:191], v[120:123]
	v_mfma_f32_16x16x32_bf16 v[108:111], v[140:143], v[192:195], v[108:111]
	v_mfma_f32_16x16x32_bf16 v[108:111], v[156:159], v[196:199], v[108:111]
	v_mfma_f32_16x16x32_bf16 v[104:107], v[160:163], v[192:195], v[104:107]
	v_mfma_f32_16x16x32_bf16 v[104:107], v[164:167], v[196:199], v[104:107]
	v_mfma_f32_16x16x32_bf16 v[92:95], v[140:143], v[200:203], v[92:95]
	v_mfma_f32_16x16x32_bf16 v[92:95], v[156:159], v[204:207], v[92:95]
	v_mfma_f32_16x16x32_bf16 v[88:91], v[160:163], v[200:203], v[88:91]
	v_mfma_f32_16x16x32_bf16 v[88:91], v[164:167], v[204:207], v[88:91]
	v_mfma_f32_16x16x32_bf16 v[76:79], v[140:143], v[208:211], v[76:79]
	v_mfma_f32_16x16x32_bf16 v[76:79], v[156:159], v[212:215], v[76:79]
	v_mfma_f32_16x16x32_bf16 v[72:75], v[160:163], v[208:211], v[72:75]
	v_mfma_f32_16x16x32_bf16 v[72:75], v[164:167], v[212:215], v[72:75]
	v_mfma_f32_16x16x32_bf16 v[116:119], v[168:171], v[184:187], v[116:119]
	v_mfma_f32_16x16x32_bf16 v[116:119], v[172:175], v[188:191], v[116:119]
	v_mfma_f32_16x16x32_bf16 v[112:115], v[176:179], v[184:187], v[112:115]
	v_mfma_f32_16x16x32_bf16 v[112:115], v[180:183], v[188:191], v[112:115]
	v_mfma_f32_16x16x32_bf16 v[100:103], v[168:171], v[192:195], v[100:103]
	v_mfma_f32_16x16x32_bf16 v[100:103], v[172:175], v[196:199], v[100:103]
	v_mfma_f32_16x16x32_bf16 v[96:99], v[176:179], v[192:195], v[96:99]
	v_mfma_f32_16x16x32_bf16 v[96:99], v[180:183], v[196:199], v[96:99]
	v_mfma_f32_16x16x32_bf16 v[84:87], v[168:171], v[200:203], v[84:87]
	v_mfma_f32_16x16x32_bf16 v[84:87], v[172:175], v[204:207], v[84:87]
	v_mfma_f32_16x16x32_bf16 v[80:83], v[176:179], v[200:203], v[80:83]
	v_mfma_f32_16x16x32_bf16 v[80:83], v[180:183], v[204:207], v[80:83]
	v_mfma_f32_16x16x32_bf16 v[68:71], v[168:171], v[208:211], v[68:71]
	v_mfma_f32_16x16x32_bf16 v[68:71], v[172:175], v[212:215], v[68:71]
	s_setprio 3
	s_barrier
	v_mfma_f32_16x16x32_bf16 v[64:67], v[176:179], v[208:211], v[64:67]
	v_mfma_f32_16x16x32_bf16 v[64:67], v[180:183], v[212:215], v[64:67]
	s_setprio 0
	s_add_i32 s51, s41, s25
	s_mov_b32 m0, s51
	ds_read_b128 v[184:187], v151 offset:16384
	ds_read_b128 v[188:191], v250 offset:16384
	ds_read_b128 v[192:195], v151 offset:18432
	ds_read_b128 v[196:199], v250 offset:18432
	ds_read_b128 v[200:203], v151 offset:20480
	ds_read_b128 v[204:207], v250 offset:20480
	global_load_lds_dwordx4 v128, s[16:17]
	s_add_i32 m0, s51, 0x2000
	s_add_u32 s52, s16, 0x404000
	s_addc_u32 s53, s17, 0
	s_add_i32 s51, s42, s25
	global_load_lds_dwordx4 v130, s[16:17]
	s_mov_b32 m0, s51
	ds_read_b128 v[208:211], v151 offset:22528
	global_load_lds_dwordx4 v128, s[52:53]
	s_add_i32 m0, s51, 0x2000
	ds_read_b128 v[212:215], v250 offset:22528
	global_load_lds_dwordx4 v130, s[52:53]
	s_waitcnt vmcnt(6)
	s_waitcnt lgkmcnt(0)
	s_setprio 2
	s_barrier
	v_mfma_f32_16x16x32_bf16 v[60:63], v[140:143], v[184:187], v[60:63]
	v_mfma_f32_16x16x32_bf16 v[60:63], v[156:159], v[188:191], v[60:63]
	v_mfma_f32_16x16x32_bf16 v[56:59], v[160:163], v[184:187], v[56:59]
	v_mfma_f32_16x16x32_bf16 v[56:59], v[164:167], v[188:191], v[56:59]
	v_mfma_f32_16x16x32_bf16 v[44:47], v[140:143], v[192:195], v[44:47]
	v_mfma_f32_16x16x32_bf16 v[44:47], v[156:159], v[196:199], v[44:47]
	v_mfma_f32_16x16x32_bf16 v[40:43], v[160:163], v[192:195], v[40:43]
	v_mfma_f32_16x16x32_bf16 v[40:43], v[164:167], v[196:199], v[40:43]
	v_mfma_f32_16x16x32_bf16 v[28:31], v[140:143], v[200:203], v[28:31]
	v_mfma_f32_16x16x32_bf16 v[28:31], v[156:159], v[204:207], v[28:31]
	v_mfma_f32_16x16x32_bf16 v[24:27], v[160:163], v[200:203], v[24:27]
	v_mfma_f32_16x16x32_bf16 v[24:27], v[164:167], v[204:207], v[24:27]
	v_mfma_f32_16x16x32_bf16 v[12:15], v[140:143], v[208:211], v[12:15]
	v_mfma_f32_16x16x32_bf16 v[12:15], v[156:159], v[212:215], v[12:15]
	v_mfma_f32_16x16x32_bf16 v[8:11], v[160:163], v[208:211], v[8:11]
	v_mfma_f32_16x16x32_bf16 v[8:11], v[164:167], v[212:215], v[8:11]
	v_mfma_f32_16x16x32_bf16 v[52:55], v[168:171], v[184:187], v[52:55]
	v_mfma_f32_16x16x32_bf16 v[52:55], v[172:175], v[188:191], v[52:55]
	v_mfma_f32_16x16x32_bf16 v[48:51], v[176:179], v[184:187], v[48:51]
	v_mfma_f32_16x16x32_bf16 v[48:51], v[180:183], v[188:191], v[48:51]
	v_mfma_f32_16x16x32_bf16 v[36:39], v[168:171], v[192:195], v[36:39]
	v_mfma_f32_16x16x32_bf16 v[36:39], v[172:175], v[196:199], v[36:39]
	v_mfma_f32_16x16x32_bf16 v[32:35], v[176:179], v[192:195], v[32:35]
	v_mfma_f32_16x16x32_bf16 v[32:35], v[180:183], v[196:199], v[32:35]
	v_mfma_f32_16x16x32_bf16 v[20:23], v[168:171], v[200:203], v[20:23]
	v_mfma_f32_16x16x32_bf16 v[20:23], v[172:175], v[204:207], v[20:23]
	v_mfma_f32_16x16x32_bf16 v[16:19], v[176:179], v[200:203], v[16:19]
	v_mfma_f32_16x16x32_bf16 v[16:19], v[180:183], v[204:207], v[16:19]
	v_mfma_f32_16x16x32_bf16 v[4:7], v[168:171], v[208:211], v[4:7]
	v_mfma_f32_16x16x32_bf16 v[4:7], v[172:175], v[212:215], v[4:7]
	s_setprio 3
	s_barrier
; #define PG8_STAGE(bufoff, gbase, voff) do { _Pragma("unroll") for (int _i = 0; _i < 2; ++_i) \
;         __builtin_amdgcn_global_load_lds((const unsigned*)((const char*)(gbase) + (voff)[_i]), (LAS unsigned*)(lds + (bufoff) + ldsw + _i * 8192), 16, 0, 0); } while (0)
; #define PG8_LDA(dst, b, h) do { _Pragma("unroll") for (int m = 0; m < 4; ++m) _Pragma("unroll") for (int k = 0; k < 2; ++k) dst[m][k] = *(const LAS bf16x8*)(lds + PG8_SA(b, h) + aoff + m * 2048 + k * 1024); } while (0)
; #define PG8_LDB(dst, b, h) do { _Pragma("unroll") for (int n = 0; n < 2; ++n) _Pragma("unroll") for (int k = 0; k < 2; ++k) dst[n][k] = *(const LAS bf16x8*)(lds + PG8_SB(b, h) + boff + n * 2048 + k * 1024); } while (0)
; #define PG8_MMA(ai, bj, At, Bt) do { __builtin_amdgcn_s_setprio(3); _Pragma("unroll") for (int m = 0; m < 4; ++m) _Pragma("unroll") for (int n = 0; n < 2; ++n) _Pragma("unroll") for (int k = 0; k < 2; ++k) \
;         acc[ai][bj][m][n] = __builtin_amdgcn_mfma_f32_16x16x32_bf16(Bt[n][k], At[m][k], acc[ai][bj][m][n], 0, 0, 0); __builtin_amdgcn_s_setprio(0); } while (0)
; #define PG8_WAIT_V(n) asm volatile("s_waitcnt vmcnt(" #n ")" ::: "memory")
; #define PG8_WAIT_L(n) asm volatile("s_waitcnt lgkmcnt(" #n ")" ::: "memory")
; template <class Epi, class Sched, bool ALIGN_EPI = false, bool SP2 = false>
; __device__ __forceinline__ void gemm_phase(LAS unsigned char* lds, const Gemm g, const Sched& S, const Epi& E) {
;     ...
;             PG8_WAIT_V(8); PG8_WAIT_L(0); PG8_BAR; PG8_MMA(0, 0, At, B0); PG8_MMA(0, 1, At, B1); PG8_BAR; PG8_SCHED;
;             PG8_LDA(At, 0, 1); PG8_STAGE(PG8_SB(0, 0), b2, voffB); PG8_STAGE(PG8_SB(0, 1), b2 + hsB, voffB); PG8_STAGE(PG8_SA(0, 0), a2, voffA);
;             PG8_WAIT_V(8); PG8_WAIT_L(0); PG8_BAR; PG8_MMA(1, 0, At, B0); PG8_MMA(1, 1, At, B1); PG8_BAR; PG8_SCHED;
;             PG8_LDB(B0, 1, 0); PG8_LDB(B1, 1, 1); PG8_SCHED; PG8_LDA(At, 1, 0); PG8_STAGE(PG8_SA(0, 1), a2 + hsA, voffA);
;             PG8_WAIT_V(8); PG8_WAIT_L(0); PG8_BAR; PG8_MMA(0, 0, At, B0); PG8_MMA(0, 1, At, B1); PG8_BAR; PG8_SCHED;
;             PG8_LDA(At, 1, 1); PG8_STAGE(PG8_SB(1, 0), b3, voffB); PG8_STAGE(PG8_SB(1, 1), b3 + hsB, voffB); PG8_STAGE(PG8_SA(1, 0), a3, voffA);
;             PG8_WAIT_V(8); PG8_WAIT_L(0); PG8_BAR; PG8_MMA(1, 0, At, B0); PG8_MMA(1, 1, At, B1); PG8_BAR; PG8_SCHED;
;     ...
;         if constexpr (ALIGN_EPI) { if (wr == 0) PG8_BAR; }
	v_mfma_f32_16x16x32_bf16 v[0:3], v[176:179], v[208:211], v[0:3]
	v_mfma_f32_16x16x32_bf16 v[0:3], v[180:183], v[212:215], v[0:3]
	s_setprio 0
	s_add_i32 s51, 0, 0x18000
	s_add_i32 s52, 0, 0x1c000
	ds_read_b128 v[140:143], v246
	ds_read_b128 v[156:159], v247
	ds_read_b128 v[160:163], v246 offset:2048
	ds_read_b128 v[164:167], v247 offset:2048
	ds_read_b128 v[168:171], v248
	ds_read_b128 v[172:175], v249
	ds_read_b128 v[176:179], v248 offset:2048
	ds_read_b128 v[180:183], v249 offset:2048
	s_mov_b32 m0, s26
	ds_read_b128 v[204:207], v250 offset:36864
	global_load_lds_dwordx4 v128, s[20:21]
	s_mov_b32 m0, s27
	ds_read_b128 v[208:211], v151 offset:38912
	global_load_lds_dwordx4 v130, s[20:21]
	s_add_u32 s20, s20, 0x404000
	s_addc_u32 s21, s21, 0
	s_mov_b32 m0, s30
	ds_read_b128 v[184:187], v151 offset:32768
	ds_read_b128 v[188:191], v250 offset:32768
	ds_read_b128 v[192:195], v151 offset:34816
	ds_read_b128 v[196:199], v250 offset:34816
	ds_read_b128 v[200:203], v151 offset:36864
	global_load_lds_dwordx4 v128, s[20:21]
	s_mov_b32 m0, s31
	ds_read_b128 v[212:215], v250 offset:38912
	global_load_lds_dwordx4 v130, s[20:21]
	s_waitcnt vmcnt(8)
	s_waitcnt lgkmcnt(0)
	s_setprio 2
	s_barrier
	v_mfma_f32_16x16x32_bf16 v[124:127], v[140:143], v[184:187], v[124:127]
	v_mfma_f32_16x16x32_bf16 v[124:127], v[156:159], v[188:191], v[124:127]
	v_mfma_f32_16x16x32_bf16 v[120:123], v[160:163], v[184:187], v[120:123]
	v_mfma_f32_16x16x32_bf16 v[120:123], v[164:167], v[188:191], v[120:123]
	v_mfma_f32_16x16x32_bf16 v[108:111], v[140:143], v[192:195], v[108:111]
	v_mfma_f32_16x16x32_bf16 v[108:111], v[156:159], v[196:199], v[108:111]
	v_mfma_f32_16x16x32_bf16 v[104:107], v[160:163], v[192:195], v[104:107]
	v_mfma_f32_16x16x32_bf16 v[104:107], v[164:167], v[196:199], v[104:107]
	v_mfma_f32_16x16x32_bf16 v[92:95], v[140:143], v[200:203], v[92:95]
	v_mfma_f32_16x16x32_bf16 v[92:95], v[156:159], v[204:207], v[92:95]
	v_mfma_f32_16x16x32_bf16 v[88:91], v[160:163], v[200:203], v[88:91]
	v_mfma_f32_16x16x32_bf16 v[88:91], v[164:167], v[204:207], v[88:91]
	v_mfma_f32_16x16x32_bf16 v[76:79], v[140:143], v[208:211], v[76:79]
	v_mfma_f32_16x16x32_bf16 v[76:79], v[156:159], v[212:215], v[76:79]
	v_mfma_f32_16x16x32_bf16 v[72:75], v[160:163], v[208:211], v[72:75]
	v_mfma_f32_16x16x32_bf16 v[72:75], v[164:167], v[212:215], v[72:75]
	v_mfma_f32_16x16x32_bf16 v[116:119], v[168:171], v[184:187], v[116:119]
	v_mfma_f32_16x16x32_bf16 v[116:119], v[172:175], v[188:191], v[116:119]
	v_mfma_f32_16x16x32_bf16 v[112:115], v[176:179], v[184:187], v[112:115]
	v_mfma_f32_16x16x32_bf16 v[112:115], v[180:183], v[188:191], v[112:115]
	v_mfma_f32_16x16x32_bf16 v[100:103], v[168:171], v[192:195], v[100:103]
	v_mfma_f32_16x16x32_bf16 v[100:103], v[172:175], v[196:199], v[100:103]
	v_mfma_f32_16x16x32_bf16 v[96:99], v[176:179], v[192:195], v[96:99]
	v_mfma_f32_16x16x32_bf16 v[96:99], v[180:183], v[196:199], v[96:99]
	v_mfma_f32_16x16x32_bf16 v[84:87], v[168:171], v[200:203], v[84:87]
	v_mfma_f32_16x16x32_bf16 v[84:87], v[172:175], v[204:207], v[84:87]
	v_mfma_f32_16x16x32_bf16 v[80:83], v[176:179], v[200:203], v[80:83]
	v_mfma_f32_16x16x32_bf16 v[80:83], v[180:183], v[204:207], v[80:83]
	v_mfma_f32_16x16x32_bf16 v[68:71], v[168:171], v[208:211], v[68:71]
	v_mfma_f32_16x16x32_bf16 v[68:71], v[172:175], v[212:215], v[68:71]
	s_setprio 3
	s_barrier
	v_mfma_f32_16x16x32_bf16 v[64:67], v[176:179], v[208:211], v[64:67]
	v_mfma_f32_16x16x32_bf16 v[64:67], v[180:183], v[212:215], v[64:67]
	s_setprio 0
	s_add_i32 s20, s51, s25
	s_add_u32 s100, s16, s8
	s_addc_u32 s101, s17, s9
	s_mov_b32 m0, s20
	ds_read_b128 v[184:187], v151 offset:49152
	ds_read_b128 v[188:191], v250 offset:49152
	ds_read_b128 v[192:195], v151 offset:51200
	ds_read_b128 v[196:199], v250 offset:51200
	ds_read_b128 v[200:203], v151 offset:53248
	ds_read_b128 v[204:207], v250 offset:53248
	global_load_lds_dwordx4 v128, s[100:101]
	s_add_i32 m0, s20, 0x2000
	s_add_u32 s16, s16, 0x404080
	s_addc_u32 s17, s17, 0
	s_add_i32 s20, s52, s25
	global_load_lds_dwordx4 v130, s[100:101]
	s_mov_b32 m0, s20
	ds_read_b128 v[208:211], v151 offset:55296
	global_load_lds_dwordx4 v128, s[16:17]
	s_add_i32 m0, s20, 0x2000
	ds_read_b128 v[212:215], v250 offset:55296
	global_load_lds_dwordx4 v130, s[16:17]
	s_waitcnt vmcnt(6)
	s_waitcnt lgkmcnt(0)
	s_setprio 2
	s_barrier
	v_mfma_f32_16x16x32_bf16 v[60:63], v[140:143], v[184:187], v[60:63]
	v_mfma_f32_16x16x32_bf16 v[60:63], v[156:159], v[188:191], v[60:63]
	v_mfma_f32_16x16x32_bf16 v[56:59], v[160:163], v[184:187], v[56:59]
	v_mfma_f32_16x16x32_bf16 v[56:59], v[164:167], v[188:191], v[56:59]
	v_mfma_f32_16x16x32_bf16 v[44:47], v[140:143], v[192:195], v[44:47]
	v_mfma_f32_16x16x32_bf16 v[44:47], v[156:159], v[196:199], v[44:47]
	v_mfma_f32_16x16x32_bf16 v[40:43], v[160:163], v[192:195], v[40:43]
	v_mfma_f32_16x16x32_bf16 v[40:43], v[164:167], v[196:199], v[40:43]
	v_mfma_f32_16x16x32_bf16 v[28:31], v[140:143], v[200:203], v[28:31]
	v_mfma_f32_16x16x32_bf16 v[28:31], v[156:159], v[204:207], v[28:31]
	v_mfma_f32_16x16x32_bf16 v[24:27], v[160:163], v[200:203], v[24:27]
	v_mfma_f32_16x16x32_bf16 v[24:27], v[164:167], v[204:207], v[24:27]
	v_mfma_f32_16x16x32_bf16 v[12:15], v[140:143], v[208:211], v[12:15]
	v_mfma_f32_16x16x32_bf16 v[12:15], v[156:159], v[212:215], v[12:15]
	v_mfma_f32_16x16x32_bf16 v[8:11], v[160:163], v[208:211], v[8:11]
	v_mfma_f32_16x16x32_bf16 v[8:11], v[164:167], v[212:215], v[8:11]
	v_mfma_f32_16x16x32_bf16 v[52:55], v[168:171], v[184:187], v[52:55]
	v_mfma_f32_16x16x32_bf16 v[52:55], v[172:175], v[188:191], v[52:55]
	v_mfma_f32_16x16x32_bf16 v[48:51], v[176:179], v[184:187], v[48:51]
	v_mfma_f32_16x16x32_bf16 v[48:51], v[180:183], v[188:191], v[48:51]
	v_mfma_f32_16x16x32_bf16 v[36:39], v[168:171], v[192:195], v[36:39]
	v_mfma_f32_16x16x32_bf16 v[36:39], v[172:175], v[196:199], v[36:39]
	v_mfma_f32_16x16x32_bf16 v[32:35], v[176:179], v[192:195], v[32:35]
	v_mfma_f32_16x16x32_bf16 v[32:35], v[180:183], v[196:199], v[32:35]
	v_mfma_f32_16x16x32_bf16 v[20:23], v[168:171], v[200:203], v[20:23]
	v_mfma_f32_16x16x32_bf16 v[20:23], v[172:175], v[204:207], v[20:23]
	v_mfma_f32_16x16x32_bf16 v[16:19], v[176:179], v[200:203], v[16:19]
	v_mfma_f32_16x16x32_bf16 v[16:19], v[180:183], v[204:207], v[16:19]
	v_mfma_f32_16x16x32_bf16 v[4:7], v[168:171], v[208:211], v[4:7]
	v_mfma_f32_16x16x32_bf16 v[4:7], v[172:175], v[212:215], v[4:7]
	s_setprio 3
	s_barrier
	v_mfma_f32_16x16x32_bf16 v[0:3], v[176:179], v[208:211], v[0:3]
	v_mfma_f32_16x16x32_bf16 v[0:3], v[180:183], v[212:215], v[0:3]
	s_setprio 0
	s_add_i32 s50, s50, 2
	s_add_u32 s14, s14, 0x100
	s_addc_u32 s15, s15, 0
	s_add_u32 s48, s48, 0x100
	s_addc_u32 s49, s49, 0
	s_cmpk_gt_u32 s50, 0xfd
	s_cbranch_scc0 .LBB0_350
	s_and_b64 vcc, exec, s[10:11]
	s_cbranch_vccz .LBB0_353
	s_barrier
